# wave all-reduce butterflies in conv_pair, conv_item, ret_sample_pair and retout: DPP quad_perm/row_half_mirror/row_mirror and v_permlane16/32_swap instead of ds_bpermute round trips
# speedup vs baseline: 1.0376x; 1.0015x over previous
.LBB0_444:
	s_cmpk_gt_i32 s30, 0xff
	s_mov_b64 s[0:1], -1
	s_cbranch_scc0 .LBB0_463
	s_cmpk_gt_u32 s30, 0x17f
	s_cbranch_scc0 .LBB0_457
	s_cmpk_gt_u32 s30, 0x27f
	s_cbranch_scc0 .LBB0_454
	v_mov_b32_e32 v6, v226
	s_lshl_b32 s0, s30, 1
	v_readfirstlane_b32 s21, v6
	s_ashr_i32 s22, s21, 8
	s_add_i32 s0, s0, s22
	s_add_i32 s20, s0, 0xfffffb00
	s_and_b32 s40, s20, 3
	v_cvt_f32_ubyte0_e32 v0, s40
	v_sub_f32_e32 v0, 0xc0a00000, v0
	v_cmp_gt_f32_e32 vcc, s3, v0
	s_and_b64 s[0:1], vcc, exec
	s_cselect_b32 s0, 0xffffffc0, 0
	v_cndmask_b32_e32 v1, 0, v233, vcc
	v_add_f32_e32 v0, v0, v1
	v_exp_f32_e32 v0, v0
	v_and_b32_e32 v7, 0xff, v6
	s_bfe_u32 s23, s21, 0x20006
	v_and_b32_e32 v125, 63, v6
	v_ldexp_f32 v0, v0, s0
	s_lshl_b32 s0, s22, 15
	s_add_i32 s31, s0, 0
	s_and_b32 s0, s20, -4
	v_sub_f32_e32 v8, 1.0, v0
	s_addk_i32 s0, 0x4000
	v_and_b32_e32 v0, 0x7f, v6
	s_lshl_b32 s22, s40, 7
	s_ashr_i32 s1, s0, 31
	v_or_b32_e32 v4, s22, v0
	v_bfe_u32 v0, v6, 7, 1
	v_or_b32_e32 v0, s0, v0
	v_mov_b32_e32 v1, s1
	v_lshlrev_b64 v[2:3], 10, v[0:1]
	v_or_b32_e32 v0, 0x100, v7
	v_lshlrev_b32_e32 v9, 1, v4
	v_lshrrev_b32_e32 v0, 7, v0
	v_or_b32_e32 v2, v2, v9
	v_or_b32_e32 v0, s0, v0
	v_lshl_add_u64 v[4:5], s[38:39], 0, v[2:3]
	v_lshlrev_b64 v[0:1], 10, v[0:1]
	global_load_ushort v10, v[4:5], off
	v_lshl_add_u64 v[4:5], s[50:51], 0, v[2:3]
	v_lshl_add_u64 v[2:3], s[90:91], 0, v[2:3]
	v_or_b32_e32 v0, v0, v9
	global_load_ushort v4, v[4:5], off
	v_log_f32_e32 v124, v8
	global_load_ushort v5, v[2:3], off
	v_lshl_add_u64 v[2:3], s[38:39], 0, v[0:1]
	global_load_ushort v9, v[2:3], off
	v_lshl_add_u64 v[2:3], s[50:51], 0, v[0:1]
	v_lshl_add_u64 v[0:1], s[90:91], 0, v[0:1]
	global_load_ushort v11, v[2:3], off
	global_load_ushort v12, v[0:1], off
	s_or_b32 s98, s0, s23
	s_mov_b32 s99, s1
	s_lshl_b64 s[98:99], s[98:99], 10
	s_add_u32 s98, s54, s98
	s_addc_u32 s99, s55, s99
	s_lshl_b32 s100, s40, 8
	s_add_u32 s98, s98, s100
	s_addc_u32 s99, s99, 0
	v_lshlrev_b32_e32 v99, 1, v125
	global_load_ushort v122, v99, s[98:99]
	global_load_ushort v123, v99, s[98:99] offset:128
	s_ashr_i32 s101, s20, 31
	s_mov_b32 s100, s20
	s_lshl_b64 s[100:101], s[100:101], 16
	s_add_u32 s100, s24, s100
	s_addc_u32 s101, s25, s101
	v_lshlrev_b32_e32 v200, 4, v6
	v_bfe_u32 v201, v6, 5, 3
	v_and_b32_e32 v200, 0x1f0, v200
	v_lshl_or_b32 v200, v201, 13, v200
	global_load_dwordx4 v[76:79], v200, s[100:101] nt
	global_load_dwordx4 v[72:75], v200, s[100:101] offset:512 nt
	global_load_dwordx4 v[68:71], v200, s[100:101] offset:1024 nt
	global_load_dwordx4 v[64:67], v200, s[100:101] offset:1536 nt
	global_load_dwordx4 v[60:63], v200, s[100:101] offset:2048 nt
	global_load_dwordx4 v[56:59], v200, s[100:101] offset:2560 nt
	global_load_dwordx4 v[52:55], v200, s[100:101] offset:3072 nt
	global_load_dwordx4 v[48:51], v200, s[100:101] offset:3584 nt
	s_add_u32 s100, s100, 0x1000
	s_addc_u32 s101, s101, 0
	global_load_dwordx4 v[44:47], v200, s[100:101] nt
	global_load_dwordx4 v[40:43], v200, s[100:101] offset:512 nt
	global_load_dwordx4 v[36:39], v200, s[100:101] offset:1024 nt
	global_load_dwordx4 v[32:35], v200, s[100:101] offset:1536 nt
	global_load_dwordx4 v[28:31], v200, s[100:101] offset:2048 nt
	global_load_dwordx4 v[24:27], v200, s[100:101] offset:2560 nt
	global_load_dwordx4 v[20:23], v200, s[100:101] offset:3072 nt
	global_load_dwordx4 v[16:19], v200, s[100:101] offset:3584 nt
	s_waitcnt vmcnt(18)
	v_lshl_add_u32 v1, v7, 2, s31
	v_lshlrev_b32_e32 v0, 16, v10
	v_lshlrev_b32_e32 v2, 16, v4
	v_lshlrev_b32_e32 v4, 16, v9
	ds_write2st64_b32 v1, v0, v4 offset1:4
	v_lshlrev_b32_e32 v0, 16, v11
	v_lshlrev_b32_e32 v3, 16, v5
	ds_write2st64_b32 v1, v2, v0 offset0:8 offset1:12
	v_lshlrev_b32_e32 v0, 16, v12
	ds_write2st64_b32 v1, v3, v0 offset0:16 offset1:20
	s_or_b32 s0, s0, s23
	v_add_f32_e32 v0, v124, v124
	s_lshl_b64 s[34:35], s[0:1], 10
	v_cmp_gt_f32_e32 vcc, s3, v0
	s_add_u32 s21, s54, s34
	s_addc_u32 s35, s55, s35
	v_cndmask_b32_e32 v0, 0, v233, vcc
	s_lshl_b32 s34, s40, 8
	v_fmac_f32_e32 v0, 2.0, v124
	s_add_u32 s34, s21, s34
	v_exp_f32_e32 v0, v0
	s_addc_u32 s35, s35, 0
	v_lshlrev_b32_e32 v99, 1, v125
	s_and_b64 s[34:35], vcc, exec
	s_cselect_b32 s21, 0xffffffc0, 0
	v_ldexp_f32 v128, v0, s21
	s_ashr_i32 s21, s20, 31
	s_lshl_b64 s[20:21], s[20:21], 16
	s_add_u32 s34, s24, s20
	v_lshlrev_b32_e32 v0, 4, v6
	v_bfe_u32 v126, v6, 5, 3
	s_addc_u32 s35, s25, s21
	v_and_b32_e32 v208, 0x1f0, v0
	v_lshlrev_b32_e32 v96, 13, v126
	v_mov_b32_e32 v97, v209
	v_add_u32_e32 v127, s31, v208
	s_waitcnt lgkmcnt(0)
	s_barrier
	ds_read_b128 v[12:15], v127 offset:4096
	ds_read_b128 v[8:11], v127 offset:4608
	ds_read_b128 v[4:7], v127 offset:5120
	ds_read_b128 v[0:3], v127 offset:5632
	s_movk_i32 s34, 0x1000
	v_mul_f32_e32 v80, 4.0, v124
	s_nop 0
	v_cmp_gt_f32_e32 vcc, s3, v80
	v_mul_f32_e32 v81, 0x40400000, v124
	s_and_b64 s[34:35], vcc, exec
	v_cndmask_b32_e32 v80, 0, v233, vcc
	v_fmac_f32_e32 v80, 4.0, v124
	v_exp_f32_e32 v80, v80
	s_cselect_b32 s34, 0xffffffc0, 0
	v_cmp_gt_f32_e32 vcc, s3, v81
	v_lshl_add_u32 v131, v126, 6, s31
	v_ldexp_f32 v98, v80, s34
	v_cndmask_b32_e32 v80, 0, v233, vcc
	v_fmac_f32_e32 v80, 0x40400000, v124
	v_exp_f32_e32 v80, v80
	s_and_b64 s[34:35], vcc, exec
	s_cselect_b32 s34, 0xffffffc0, 0
	v_cmp_gt_f32_e32 vcc, s3, v124
	v_ldexp_f32 v130, v80, s34
	s_nop 0
	v_cndmask_b32_e32 v80, 0, v233, vcc
	v_add_f32_e32 v80, v124, v80
	v_exp_f32_e32 v80, v80
	s_and_b64 s[34:35], vcc, exec
	ds_read_b128 v[102:105], v131 offset:2048
	ds_read_b128 v[110:113], v131 offset:3072
	s_cselect_b32 s34, 0xffffffc0, 0
	v_ldexp_f32 v129, v80, s34
	ds_read_b128 v[80:83], v131
	ds_read_b128 v[84:87], v131 offset:512
	ds_read_b128 v[88:91], v131 offset:1024
	ds_read_b128 v[92:95], v131 offset:1536
	s_waitcnt lgkmcnt(5)
	v_mul_f32_e32 v102, v130, v102
	v_pk_mul_f32 v[106:107], v[12:13], v[102:103] op_sel_hi:[1,0]
	v_pk_mul_f32 v[108:109], v[14:15], v[102:103] op_sel_hi:[1,0]
	ds_read_b128 v[114:117], v131 offset:3584
	s_add_u32 s20, s26, s20
	s_addc_u32 s21, s27, s21
	v_lshl_add_u64 v[100:101], s[20:21], 0, v[208:209]
	v_lshl_add_u64 v[144:145], v[100:101], 0, v[96:97]
	v_or_b32_e32 v208, 0x200, v96
	s_add_i32 s20, s23, 1
	s_lshl_b32 s34, s23, 9
	s_waitcnt vmcnt(15) lgkmcnt(4)
	v_pk_fma_f32 v[118:119], v[78:79], v[80:81], 0 op_sel_hi:[1,0,0]
	v_pk_fma_f32 v[120:121], v[76:77], v[80:81], 0 op_sel_hi:[1,0,0]
	s_waitcnt lgkmcnt(3)
	v_pk_fma_f32 v[132:133], v[78:79], v[84:85], 0 op_sel_hi:[1,0,0]
	v_pk_fma_f32 v[134:135], v[76:77], v[84:85], 0 op_sel_hi:[1,0,0]
	s_waitcnt lgkmcnt(2)
	v_pk_fma_f32 v[136:137], v[78:79], v[88:89], 0 op_sel_hi:[1,0,0]
	v_pk_fma_f32 v[138:139], v[76:77], v[88:89], 0 op_sel_hi:[1,0,0]
	s_waitcnt lgkmcnt(1)
	v_pk_fma_f32 v[140:141], v[78:79], v[92:93], 0 op_sel_hi:[1,0,0]
	v_pk_fma_f32 v[142:143], v[76:77], v[92:93], 0 op_sel_hi:[1,0,0]
	v_pk_fma_f32 v[78:79], v[98:99], v[78:79], v[108:109] op_sel_hi:[0,1,1]
	v_pk_fma_f32 v[76:77], v[98:99], v[76:77], v[106:107] op_sel_hi:[0,1,1]
	ds_read_b128 v[106:109], v131 offset:2560
	s_waitcnt lgkmcnt(0)
	v_mul_f32_e32 v102, v128, v106
	v_pk_fma_f32 v[78:79], v[10:11], v[102:103], v[78:79] op_sel_hi:[1,0,1]
	v_pk_fma_f32 v[76:77], v[8:9], v[102:103], v[76:77] op_sel_hi:[1,0,1]
	v_mul_f32_e32 v102, v129, v110
	v_pk_fma_f32 v[78:79], v[6:7], v[102:103], v[78:79] op_sel_hi:[1,0,1]
	v_pk_fma_f32 v[76:77], v[4:5], v[102:103], v[76:77] op_sel_hi:[1,0,1]
	v_pk_fma_f32 v[78:79], v[2:3], v[114:115], v[78:79] op_sel_hi:[1,0,1]
	v_pk_fma_f32 v[76:77], v[0:1], v[114:115], v[76:77] op_sel_hi:[1,0,1]
	v_mul_f32_e32 v102, v130, v103
	global_store_dwordx4 v[144:145], v[76:79], off nt
	s_waitcnt vmcnt(15)
	s_nop 0
	v_pk_fma_f32 v[76:77], v[74:75], v[80:81], v[118:119] op_sel:[0,1,0]
	v_pk_fma_f32 v[78:79], v[72:73], v[80:81], v[120:121] op_sel:[0,1,0]
	v_pk_fma_f32 v[80:81], v[74:75], v[84:85], v[132:133] op_sel:[0,1,0]
	v_pk_mul_f32 v[132:133], v[12:13], v[102:103] op_sel_hi:[1,0]
	v_pk_mul_f32 v[102:103], v[14:15], v[102:103] op_sel_hi:[1,0]
	v_pk_fma_f32 v[84:85], v[72:73], v[84:85], v[134:135] op_sel:[0,1,0]
	v_pk_fma_f32 v[118:119], v[74:75], v[88:89], v[136:137] op_sel:[0,1,0]
	v_pk_fma_f32 v[88:89], v[72:73], v[88:89], v[138:139] op_sel:[0,1,0]
	v_pk_fma_f32 v[120:121], v[74:75], v[92:93], v[140:141] op_sel:[0,1,0]
	v_pk_fma_f32 v[92:93], v[72:73], v[92:93], v[142:143] op_sel:[0,1,0]
	v_pk_fma_f32 v[74:75], v[98:99], v[74:75], v[102:103] op_sel_hi:[0,1,1]
	v_pk_fma_f32 v[72:73], v[98:99], v[72:73], v[132:133] op_sel_hi:[0,1,1]
	v_mul_f32_e32 v102, v128, v107
	v_pk_fma_f32 v[74:75], v[10:11], v[102:103], v[74:75] op_sel_hi:[1,0,1]
	v_pk_fma_f32 v[72:73], v[8:9], v[102:103], v[72:73] op_sel_hi:[1,0,1]
	v_mul_f32_e32 v102, v129, v111
	v_pk_fma_f32 v[74:75], v[6:7], v[102:103], v[74:75] op_sel_hi:[1,0,1]
	v_pk_fma_f32 v[72:73], v[4:5], v[102:103], v[72:73] op_sel_hi:[1,0,1]
	v_pk_fma_f32 v[74:75], v[2:3], v[114:115], v[74:75] op_sel:[0,1,0]
	v_pk_fma_f32 v[72:73], v[0:1], v[114:115], v[72:73] op_sel:[0,1,0]
	v_lshl_add_u64 v[102:103], v[100:101], 0, v[208:209]
	global_store_dwordx4 v[102:103], v[72:75], off nt
	s_waitcnt vmcnt(15)
	v_pk_fma_f32 v[92:93], v[68:69], v[94:95], v[92:93] op_sel_hi:[1,0,1]
	v_or_b32_e32 v208, 0x400, v96
	v_pk_fma_f32 v[72:73], v[70:71], v[82:83], v[76:77] op_sel_hi:[1,0,1]
	v_pk_fma_f32 v[74:75], v[68:69], v[82:83], v[78:79] op_sel_hi:[1,0,1]
	v_mul_f32_e32 v82, v130, v104
	v_pk_mul_f32 v[102:103], v[12:13], v[82:83] op_sel_hi:[1,0]
	v_pk_mul_f32 v[106:107], v[14:15], v[82:83] op_sel_hi:[1,0]
	v_pk_fma_f32 v[76:77], v[70:71], v[86:87], v[80:81] op_sel_hi:[1,0,1]
	v_pk_fma_f32 v[78:79], v[68:69], v[86:87], v[84:85] op_sel_hi:[1,0,1]
	v_pk_fma_f32 v[80:81], v[70:71], v[90:91], v[118:119] op_sel_hi:[1,0,1]
	v_pk_fma_f32 v[84:85], v[68:69], v[90:91], v[88:89] op_sel_hi:[1,0,1]
	v_pk_fma_f32 v[88:89], v[70:71], v[94:95], v[120:121] op_sel_hi:[1,0,1]
	v_pk_fma_f32 v[70:71], v[98:99], v[70:71], v[106:107] op_sel_hi:[0,1,1]
	v_pk_fma_f32 v[68:69], v[98:99], v[68:69], v[102:103] op_sel_hi:[0,1,1]
	v_mul_f32_e32 v82, v128, v108
	v_pk_fma_f32 v[70:71], v[10:11], v[82:83], v[70:71] op_sel_hi:[1,0,1]
	v_pk_fma_f32 v[68:69], v[8:9], v[82:83], v[68:69] op_sel_hi:[1,0,1]
	v_mul_f32_e32 v82, v129, v112
	v_pk_fma_f32 v[70:71], v[6:7], v[82:83], v[70:71] op_sel_hi:[1,0,1]
	v_pk_fma_f32 v[68:69], v[4:5], v[82:83], v[68:69] op_sel_hi:[1,0,1]
	v_pk_fma_f32 v[70:71], v[2:3], v[116:117], v[70:71] op_sel_hi:[1,0,1]
	v_pk_fma_f32 v[68:69], v[0:1], v[116:117], v[68:69] op_sel_hi:[1,0,1]
	v_lshl_add_u64 v[102:103], v[100:101], 0, v[208:209]
	global_store_dwordx4 v[102:103], v[68:71], off nt
	v_or_b32_e32 v208, 0x600, v96
	s_nop 0
	v_mov_b32_e32 v68, v83
	s_waitcnt vmcnt(15)
	v_pk_fma_f32 v[72:73], v[66:67], v[68:69], v[72:73] op_sel_hi:[1,0,1]
	v_pk_fma_f32 v[74:75], v[64:65], v[68:69], v[74:75] op_sel_hi:[1,0,1]
	v_mov_b32_e32 v68, v87
	v_pk_fma_f32 v[76:77], v[66:67], v[68:69], v[76:77] op_sel_hi:[1,0,1]
	v_pk_fma_f32 v[78:79], v[64:65], v[68:69], v[78:79] op_sel_hi:[1,0,1]
	v_mov_b32_e32 v68, v91
	v_pk_fma_f32 v[80:81], v[66:67], v[68:69], v[80:81] op_sel_hi:[1,0,1]
	v_pk_fma_f32 v[82:83], v[64:65], v[68:69], v[84:85] op_sel_hi:[1,0,1]
	v_mov_b32_e32 v68, v95
	v_pk_fma_f32 v[84:85], v[66:67], v[68:69], v[88:89] op_sel_hi:[1,0,1]
	v_pk_fma_f32 v[86:87], v[64:65], v[68:69], v[92:93] op_sel_hi:[1,0,1]
	v_mul_f32_e32 v68, v130, v105
	v_pk_mul_f32 v[70:71], v[12:13], v[68:69] op_sel_hi:[1,0]
	v_pk_mul_f32 v[68:69], v[14:15], v[68:69] op_sel_hi:[1,0]
	v_pk_fma_f32 v[64:65], v[98:99], v[64:65], v[70:71] op_sel_hi:[0,1,1]
	v_pk_fma_f32 v[66:67], v[98:99], v[66:67], v[68:69] op_sel_hi:[0,1,1]
	v_mul_f32_e32 v68, v128, v109
	v_pk_fma_f32 v[66:67], v[10:11], v[68:69], v[66:67] op_sel_hi:[1,0,1]
	v_pk_fma_f32 v[64:65], v[8:9], v[68:69], v[64:65] op_sel_hi:[1,0,1]
	v_mul_f32_e32 v68, v129, v113
	v_pk_fma_f32 v[66:67], v[6:7], v[68:69], v[66:67] op_sel_hi:[1,0,1]
	v_pk_fma_f32 v[64:65], v[4:5], v[68:69], v[64:65] op_sel_hi:[1,0,1]
	v_mov_b32_e32 v68, v117
	v_pk_fma_f32 v[66:67], v[2:3], v[68:69], v[66:67] op_sel_hi:[1,0,1]
	v_pk_fma_f32 v[64:65], v[0:1], v[68:69], v[64:65] op_sel_hi:[1,0,1]
	v_lshl_add_u64 v[68:69], v[100:101], 0, v[208:209]
	global_store_dwordx4 v[68:69], v[64:67], off nt
	ds_read_b128 v[68:71], v131 offset:16
	ds_read_b128 v[64:67], v131 offset:32
	v_or_b32_e32 v208, 0x800, v96
	s_waitcnt vmcnt(15) lgkmcnt(1)
	v_pk_fma_f32 v[102:103], v[62:63], v[68:69], v[72:73] op_sel_hi:[1,0,1]
	v_pk_fma_f32 v[104:105], v[60:61], v[68:69], v[74:75] op_sel_hi:[1,0,1]
	ds_read_b128 v[72:75], v131 offset:528
	s_waitcnt vmcnt(14)
	v_pk_fma_f32 v[102:103], v[58:59], v[68:69], v[102:103] op_sel:[0,1,0]
	v_pk_fma_f32 v[68:69], v[56:57], v[68:69], v[104:105] op_sel:[0,1,0]
	s_waitcnt lgkmcnt(0)
	v_pk_fma_f32 v[106:107], v[62:63], v[72:73], v[76:77] op_sel_hi:[1,0,1]
	v_pk_fma_f32 v[108:109], v[60:61], v[72:73], v[78:79] op_sel_hi:[1,0,1]
	ds_read_b128 v[76:79], v131 offset:1040
	v_pk_fma_f32 v[104:105], v[58:59], v[72:73], v[106:107] op_sel:[0,1,0]
	v_pk_fma_f32 v[72:73], v[56:57], v[72:73], v[108:109] op_sel:[0,1,0]
	s_waitcnt lgkmcnt(0)
	v_pk_fma_f32 v[110:111], v[62:63], v[76:77], v[80:81] op_sel_hi:[1,0,1]
	v_pk_fma_f32 v[112:113], v[60:61], v[76:77], v[82:83] op_sel_hi:[1,0,1]
	ds_read_b128 v[80:83], v131 offset:1552
	v_pk_fma_f32 v[106:107], v[58:59], v[76:77], v[110:111] op_sel:[0,1,0]
	v_pk_fma_f32 v[76:77], v[56:57], v[76:77], v[112:113] op_sel:[0,1,0]
	s_waitcnt lgkmcnt(0)
	v_pk_fma_f32 v[114:115], v[62:63], v[80:81], v[84:85] op_sel_hi:[1,0,1]
	v_pk_fma_f32 v[116:117], v[60:61], v[80:81], v[86:87] op_sel_hi:[1,0,1]
	ds_read_b128 v[84:87], v131 offset:2064
	v_pk_fma_f32 v[108:109], v[58:59], v[80:81], v[114:115] op_sel:[0,1,0]
	v_pk_fma_f32 v[80:81], v[56:57], v[80:81], v[116:117] op_sel:[0,1,0]
	s_waitcnt vmcnt(13)
	v_pk_fma_f32 v[76:77], v[52:53], v[78:79], v[76:77] op_sel_hi:[1,0,1]
	v_pk_fma_f32 v[80:81], v[52:53], v[82:83], v[80:81] op_sel_hi:[1,0,1]
	s_waitcnt lgkmcnt(0)
	v_mul_f32_e32 v84, v130, v84
	v_pk_mul_f32 v[88:89], v[12:13], v[84:85] op_sel_hi:[1,0]
	v_pk_mul_f32 v[90:91], v[14:15], v[84:85] op_sel_hi:[1,0]
	v_pk_fma_f32 v[88:89], v[98:99], v[60:61], v[88:89] op_sel_hi:[0,1,1]
	v_pk_fma_f32 v[90:91], v[98:99], v[62:63], v[90:91] op_sel_hi:[0,1,1]
	ds_read_b128 v[60:63], v131 offset:2576
	s_waitcnt lgkmcnt(0)
	v_mul_f32_e32 v60, v128, v60
	v_pk_fma_f32 v[92:93], v[10:11], v[60:61], v[90:91] op_sel_hi:[1,0,1]
	v_pk_fma_f32 v[94:95], v[8:9], v[60:61], v[88:89] op_sel_hi:[1,0,1]
	ds_read_b128 v[88:91], v131 offset:3088
	v_mul_f32_e32 v62, v128, v62
	s_waitcnt lgkmcnt(0)
	v_mul_f32_e32 v60, v129, v88
	v_pk_fma_f32 v[118:119], v[6:7], v[60:61], v[92:93] op_sel_hi:[1,0,1]
	v_pk_fma_f32 v[120:121], v[4:5], v[60:61], v[94:95] op_sel_hi:[1,0,1]
	ds_read_b128 v[92:95], v131 offset:3600
	v_mul_f32_e32 v60, v130, v85
	v_pk_mul_f32 v[84:85], v[12:13], v[60:61] op_sel_hi:[1,0]
	v_pk_mul_f32 v[110:111], v[14:15], v[60:61] op_sel_hi:[1,0]
	v_pk_fma_f32 v[56:57], v[98:99], v[56:57], v[84:85] op_sel_hi:[0,1,1]
	v_pk_fma_f32 v[58:59], v[98:99], v[58:59], v[110:111] op_sel_hi:[0,1,1]
	v_mul_f32_e32 v60, v128, v61
	v_pk_fma_f32 v[58:59], v[10:11], v[60:61], v[58:59] op_sel_hi:[1,0,1]
	v_pk_fma_f32 v[56:57], v[8:9], v[60:61], v[56:57] op_sel_hi:[1,0,1]
	v_mul_f32_e32 v60, v129, v89
	s_waitcnt lgkmcnt(0)
	v_pk_fma_f32 v[134:135], v[2:3], v[92:93], v[118:119] op_sel_hi:[1,0,1]
	v_lshl_add_u64 v[118:119], v[100:101], 0, v[208:209]
	v_pk_fma_f32 v[58:59], v[6:7], v[60:61], v[58:59] op_sel_hi:[1,0,1]
	v_pk_fma_f32 v[56:57], v[4:5], v[60:61], v[56:57] op_sel_hi:[1,0,1]
	v_or_b32_e32 v208, 0xa00, v96
	v_pk_fma_f32 v[58:59], v[2:3], v[92:93], v[58:59] op_sel:[0,1,0]
	v_pk_fma_f32 v[56:57], v[0:1], v[92:93], v[56:57] op_sel:[0,1,0]
	v_lshl_add_u64 v[60:61], v[100:101], 0, v[208:209]
	global_store_dwordx4 v[60:61], v[56:59], off nt
	v_pk_fma_f32 v[132:133], v[0:1], v[92:93], v[120:121] op_sel_hi:[1,0,1]
	v_pk_fma_f32 v[60:61], v[54:55], v[74:75], v[104:105] op_sel_hi:[1,0,1]
	v_pk_fma_f32 v[56:57], v[54:55], v[70:71], v[102:103] op_sel_hi:[1,0,1]
	v_pk_fma_f32 v[58:59], v[52:53], v[70:71], v[68:69] op_sel_hi:[1,0,1]
	v_mul_f32_e32 v70, v130, v86
	v_pk_mul_f32 v[88:89], v[12:13], v[70:71] op_sel_hi:[1,0]
	v_pk_mul_f32 v[92:93], v[14:15], v[70:71] op_sel_hi:[1,0]
	v_pk_fma_f32 v[68:69], v[52:53], v[74:75], v[72:73] op_sel_hi:[1,0,1]
	v_pk_fma_f32 v[72:73], v[54:55], v[78:79], v[106:107] op_sel_hi:[1,0,1]
	v_pk_fma_f32 v[84:85], v[54:55], v[82:83], v[108:109] op_sel_hi:[1,0,1]
	v_pk_fma_f32 v[54:55], v[98:99], v[54:55], v[92:93] op_sel_hi:[0,1,1]
	v_pk_fma_f32 v[52:53], v[98:99], v[52:53], v[88:89] op_sel_hi:[0,1,1]
	v_pk_fma_f32 v[54:55], v[10:11], v[62:63], v[54:55] op_sel_hi:[1,0,1]
	v_pk_fma_f32 v[52:53], v[8:9], v[62:63], v[52:53] op_sel_hi:[1,0,1]
	v_mul_f32_e32 v62, v129, v90
	v_pk_fma_f32 v[54:55], v[6:7], v[62:63], v[54:55] op_sel_hi:[1,0,1]
	v_pk_fma_f32 v[52:53], v[4:5], v[62:63], v[52:53] op_sel_hi:[1,0,1]
	v_or_b32_e32 v208, 0xc00, v96
	v_pk_fma_f32 v[54:55], v[2:3], v[94:95], v[54:55] op_sel_hi:[1,0,1]
	v_pk_fma_f32 v[52:53], v[0:1], v[94:95], v[52:53] op_sel_hi:[1,0,1]
	v_lshl_add_u64 v[88:89], v[100:101], 0, v[208:209]
	global_store_dwordx4 v[88:89], v[52:55], off nt
	v_mov_b32_e32 v62, v83
	v_or_b32_e32 v208, 0xe00, v96
	v_mov_b32_e32 v52, v71
	s_waitcnt vmcnt(14)
	v_pk_fma_f32 v[54:55], v[50:51], v[52:53], v[56:57] op_sel_hi:[1,0,1]
	v_mov_b32_e32 v56, v75
	v_pk_fma_f32 v[52:53], v[48:49], v[52:53], v[58:59] op_sel_hi:[1,0,1]
	v_pk_fma_f32 v[58:59], v[50:51], v[56:57], v[60:61] op_sel_hi:[1,0,1]
	v_mov_b32_e32 v60, v79
	v_pk_fma_f32 v[56:57], v[48:49], v[56:57], v[68:69] op_sel_hi:[1,0,1]
	v_pk_fma_f32 v[68:69], v[50:51], v[60:61], v[72:73] op_sel_hi:[1,0,1]
	v_pk_fma_f32 v[70:71], v[50:51], v[62:63], v[84:85] op_sel_hi:[1,0,1]
	v_pk_fma_f32 v[72:73], v[48:49], v[62:63], v[80:81] op_sel_hi:[1,0,1]
	v_mul_f32_e32 v62, v130, v87
	v_pk_fma_f32 v[60:61], v[48:49], v[60:61], v[76:77] op_sel_hi:[1,0,1]
	v_pk_mul_f32 v[74:75], v[12:13], v[62:63] op_sel_hi:[1,0]
	v_pk_mul_f32 v[76:77], v[14:15], v[62:63] op_sel_hi:[1,0]
	v_pk_fma_f32 v[48:49], v[98:99], v[48:49], v[74:75] op_sel_hi:[0,1,1]
	v_pk_fma_f32 v[50:51], v[98:99], v[50:51], v[76:77] op_sel_hi:[0,1,1]
	v_mul_f32_e32 v62, v128, v63
	v_pk_fma_f32 v[50:51], v[10:11], v[62:63], v[50:51] op_sel_hi:[1,0,1]
	v_pk_fma_f32 v[48:49], v[8:9], v[62:63], v[48:49] op_sel_hi:[1,0,1]
	v_mul_f32_e32 v62, v129, v91
	v_pk_fma_f32 v[50:51], v[6:7], v[62:63], v[50:51] op_sel_hi:[1,0,1]
	v_pk_fma_f32 v[48:49], v[4:5], v[62:63], v[48:49] op_sel_hi:[1,0,1]
	v_mov_b32_e32 v62, v95
	v_pk_fma_f32 v[50:51], v[2:3], v[62:63], v[50:51] op_sel_hi:[1,0,1]
	v_pk_fma_f32 v[48:49], v[0:1], v[62:63], v[48:49] op_sel_hi:[1,0,1]
	v_lshl_add_u64 v[62:63], v[100:101], 0, v[208:209]
	global_store_dwordx4 v[62:63], v[48:51], off nt
	s_waitcnt vmcnt(14)
	v_pk_fma_f32 v[80:81], v[46:47], v[64:65], v[54:55] op_sel_hi:[1,0,1]
	v_pk_fma_f32 v[82:83], v[44:45], v[64:65], v[52:53] op_sel_hi:[1,0,1]
	ds_read_b128 v[48:51], v131 offset:544
	ds_read_b128 v[52:55], v131 offset:1056
	ds_read_b128 v[76:79], v131 offset:3616
	v_or_b32_e32 v208, 0x1000, v96
	v_lshl_add_u64 v[102:103], v[100:101], 0, v[208:209]
	s_waitcnt lgkmcnt(2)
	v_pk_fma_f32 v[84:85], v[46:47], v[48:49], v[58:59] op_sel_hi:[1,0,1]
	v_pk_fma_f32 v[86:87], v[44:45], v[48:49], v[56:57] op_sel_hi:[1,0,1]
	s_waitcnt lgkmcnt(1)
	v_pk_fma_f32 v[90:91], v[44:45], v[52:53], v[60:61] op_sel_hi:[1,0,1]
	ds_read_b128 v[56:59], v131 offset:1568
	ds_read_b128 v[60:63], v131 offset:2080
	v_pk_fma_f32 v[88:89], v[46:47], v[52:53], v[68:69] op_sel_hi:[1,0,1]
	v_or_b32_e32 v208, 0x1200, v96
	global_store_dwordx4 v[118:119], v[132:135], off nt
	s_waitcnt lgkmcnt(1)
	v_pk_fma_f32 v[92:93], v[46:47], v[56:57], v[70:71] op_sel_hi:[1,0,1]
	s_waitcnt lgkmcnt(0)
	v_mul_f32_e32 v60, v130, v60
	v_pk_mul_f32 v[68:69], v[14:15], v[60:61] op_sel_hi:[1,0]
	v_pk_mul_f32 v[70:71], v[12:13], v[60:61] op_sel_hi:[1,0]
	v_pk_fma_f32 v[94:95], v[44:45], v[56:57], v[72:73] op_sel_hi:[1,0,1]
	v_pk_fma_f32 v[44:45], v[98:99], v[44:45], v[70:71] op_sel_hi:[0,1,1]
	v_pk_fma_f32 v[46:47], v[98:99], v[46:47], v[68:69] op_sel_hi:[0,1,1]
	ds_read_b128 v[68:71], v131 offset:2592
	ds_read_b128 v[72:75], v131 offset:3104
	s_waitcnt lgkmcnt(1)
	v_mul_f32_e32 v60, v128, v68
	v_pk_fma_f32 v[44:45], v[8:9], v[60:61], v[44:45] op_sel_hi:[1,0,1]
	v_pk_fma_f32 v[46:47], v[10:11], v[60:61], v[46:47] op_sel_hi:[1,0,1]
	s_waitcnt lgkmcnt(0)
	v_mul_f32_e32 v60, v129, v72
	v_pk_fma_f32 v[44:45], v[4:5], v[60:61], v[44:45] op_sel_hi:[1,0,1]
	v_pk_fma_f32 v[46:47], v[6:7], v[60:61], v[46:47] op_sel_hi:[1,0,1]
	v_pk_fma_f32 v[44:45], v[0:1], v[76:77], v[44:45] op_sel_hi:[1,0,1]
	v_pk_fma_f32 v[46:47], v[2:3], v[76:77], v[46:47] op_sel_hi:[1,0,1]
	v_mul_f32_e32 v60, v130, v61
	global_store_dwordx4 v[102:103], v[44:47], off nt
	s_waitcnt vmcnt(15)
	s_nop 0
	v_pk_fma_f32 v[44:45], v[42:43], v[64:65], v[80:81] op_sel:[0,1,0]
	v_pk_fma_f32 v[46:47], v[40:41], v[64:65], v[82:83] op_sel:[0,1,0]
	v_pk_fma_f32 v[64:65], v[42:43], v[48:49], v[84:85] op_sel:[0,1,0]
	v_pk_mul_f32 v[84:85], v[14:15], v[60:61] op_sel_hi:[1,0]
	v_pk_mul_f32 v[60:61], v[12:13], v[60:61] op_sel_hi:[1,0]
	v_pk_fma_f32 v[48:49], v[40:41], v[48:49], v[86:87] op_sel:[0,1,0]
	v_pk_fma_f32 v[80:81], v[42:43], v[52:53], v[88:89] op_sel:[0,1,0]
	v_pk_fma_f32 v[52:53], v[40:41], v[52:53], v[90:91] op_sel:[0,1,0]
	v_pk_fma_f32 v[82:83], v[42:43], v[56:57], v[92:93] op_sel:[0,1,0]
	v_pk_fma_f32 v[56:57], v[40:41], v[56:57], v[94:95] op_sel:[0,1,0]
	v_pk_fma_f32 v[40:41], v[98:99], v[40:41], v[60:61] op_sel_hi:[0,1,1]
	v_pk_fma_f32 v[42:43], v[98:99], v[42:43], v[84:85] op_sel_hi:[0,1,1]
	v_mul_f32_e32 v60, v128, v69
	v_pk_fma_f32 v[40:41], v[8:9], v[60:61], v[40:41] op_sel_hi:[1,0,1]
	v_pk_fma_f32 v[42:43], v[10:11], v[60:61], v[42:43] op_sel_hi:[1,0,1]
	v_mul_f32_e32 v60, v129, v73
	v_pk_fma_f32 v[40:41], v[4:5], v[60:61], v[40:41] op_sel_hi:[1,0,1]
	v_pk_fma_f32 v[42:43], v[6:7], v[60:61], v[42:43] op_sel_hi:[1,0,1]
	v_pk_fma_f32 v[40:41], v[0:1], v[76:77], v[40:41] op_sel:[0,1,0]
	v_pk_fma_f32 v[42:43], v[2:3], v[76:77], v[42:43] op_sel:[0,1,0]
	v_lshl_add_u64 v[60:61], v[100:101], 0, v[208:209]
	global_store_dwordx4 v[60:61], v[40:43], off nt
	s_waitcnt vmcnt(15)
	v_pk_fma_f32 v[52:53], v[36:37], v[54:55], v[52:53] op_sel_hi:[1,0,1]
	v_pk_fma_f32 v[60:61], v[38:39], v[58:59], v[82:83] op_sel_hi:[1,0,1]
	v_pk_fma_f32 v[40:41], v[38:39], v[66:67], v[44:45] op_sel_hi:[1,0,1]
	v_pk_fma_f32 v[42:43], v[36:37], v[66:67], v[46:47] op_sel_hi:[1,0,1]
	v_pk_fma_f32 v[44:45], v[38:39], v[50:51], v[64:65] op_sel_hi:[1,0,1]
	v_pk_fma_f32 v[46:47], v[36:37], v[50:51], v[48:49] op_sel_hi:[1,0,1]
	v_mul_f32_e32 v50, v130, v62
	v_pk_mul_f32 v[64:65], v[14:15], v[50:51] op_sel_hi:[1,0]
	v_pk_mul_f32 v[68:69], v[12:13], v[50:51] op_sel_hi:[1,0]
	v_pk_fma_f32 v[48:49], v[38:39], v[54:55], v[80:81] op_sel_hi:[1,0,1]
	v_pk_fma_f32 v[56:57], v[36:37], v[58:59], v[56:57] op_sel_hi:[1,0,1]
	v_pk_fma_f32 v[36:37], v[98:99], v[36:37], v[68:69] op_sel_hi:[0,1,1]
	v_pk_fma_f32 v[38:39], v[98:99], v[38:39], v[64:65] op_sel_hi:[0,1,1]
	v_mul_f32_e32 v50, v128, v70
	v_pk_fma_f32 v[36:37], v[8:9], v[50:51], v[36:37] op_sel_hi:[1,0,1]
	v_pk_fma_f32 v[38:39], v[10:11], v[50:51], v[38:39] op_sel_hi:[1,0,1]
	v_mul_f32_e32 v50, v129, v74
	v_pk_fma_f32 v[36:37], v[4:5], v[50:51], v[36:37] op_sel_hi:[1,0,1]
	v_pk_fma_f32 v[38:39], v[6:7], v[50:51], v[38:39] op_sel_hi:[1,0,1]
	v_or_b32_e32 v208, 0x1400, v96
	v_pk_fma_f32 v[36:37], v[0:1], v[78:79], v[36:37] op_sel_hi:[1,0,1]
	v_pk_fma_f32 v[38:39], v[2:3], v[78:79], v[38:39] op_sel_hi:[1,0,1]
	v_lshl_add_u64 v[64:65], v[100:101], 0, v[208:209]
	global_store_dwordx4 v[64:65], v[36:39], off nt
	v_mov_b32_e32 v50, v59
	v_or_b32_e32 v208, 0x1600, v96
	v_mov_b32_e32 v38, v67
	s_waitcnt vmcnt(15)
	v_pk_fma_f32 v[36:37], v[34:35], v[38:39], v[40:41] op_sel_hi:[1,0,1]
	v_pk_fma_f32 v[38:39], v[32:33], v[38:39], v[42:43] op_sel_hi:[1,0,1]
	v_mov_b32_e32 v42, v51
	v_pk_fma_f32 v[40:41], v[34:35], v[42:43], v[44:45] op_sel_hi:[1,0,1]
	v_pk_fma_f32 v[42:43], v[32:33], v[42:43], v[46:47] op_sel_hi:[1,0,1]
	v_mov_b32_e32 v46, v55
	v_pk_fma_f32 v[44:45], v[34:35], v[46:47], v[48:49] op_sel_hi:[1,0,1]
	v_pk_fma_f32 v[46:47], v[32:33], v[46:47], v[52:53] op_sel_hi:[1,0,1]
	v_mul_f32_e32 v52, v130, v63
	v_pk_mul_f32 v[54:55], v[14:15], v[52:53] op_sel_hi:[1,0]
	v_pk_mul_f32 v[52:53], v[12:13], v[52:53] op_sel_hi:[1,0]
	v_pk_fma_f32 v[48:49], v[34:35], v[50:51], v[60:61] op_sel_hi:[1,0,1]
	v_pk_fma_f32 v[50:51], v[32:33], v[50:51], v[56:57] op_sel_hi:[1,0,1]
	v_pk_fma_f32 v[32:33], v[98:99], v[32:33], v[52:53] op_sel_hi:[0,1,1]
	v_pk_fma_f32 v[34:35], v[98:99], v[34:35], v[54:55] op_sel_hi:[0,1,1]
	v_mul_f32_e32 v52, v128, v71
	v_pk_fma_f32 v[32:33], v[8:9], v[52:53], v[32:33] op_sel_hi:[1,0,1]
	v_pk_fma_f32 v[34:35], v[10:11], v[52:53], v[34:35] op_sel_hi:[1,0,1]
	v_mul_f32_e32 v52, v129, v75
	v_pk_fma_f32 v[32:33], v[4:5], v[52:53], v[32:33] op_sel_hi:[1,0,1]
	v_pk_fma_f32 v[34:35], v[6:7], v[52:53], v[34:35] op_sel_hi:[1,0,1]
	v_mov_b32_e32 v52, v79
	v_pk_fma_f32 v[32:33], v[0:1], v[52:53], v[32:33] op_sel_hi:[1,0,1]
	v_pk_fma_f32 v[34:35], v[2:3], v[52:53], v[34:35] op_sel_hi:[1,0,1]
	v_lshl_add_u64 v[52:53], v[100:101], 0, v[208:209]
	global_store_dwordx4 v[52:53], v[32:35], off nt
	ds_read_b128 v[32:35], v131 offset:48
	v_or_b32_e32 v208, 0x1800, v96
	v_lshl_add_u64 v[80:81], v[100:101], 0, v[208:209]
	v_or_b32_e32 v208, 0x1a00, v96
	s_waitcnt vmcnt(15) lgkmcnt(0)
	v_pk_fma_f32 v[60:61], v[30:31], v[32:33], v[36:37] op_sel_hi:[1,0,1]
	v_pk_fma_f32 v[62:63], v[28:29], v[32:33], v[38:39] op_sel_hi:[1,0,1]
	ds_read_b128 v[36:39], v131 offset:560
	s_waitcnt vmcnt(14)
	v_pk_fma_f32 v[60:61], v[26:27], v[32:33], v[60:61] op_sel:[0,1,0]
	v_pk_fma_f32 v[32:33], v[24:25], v[32:33], v[62:63] op_sel:[0,1,0]
	s_waitcnt lgkmcnt(0)
	v_pk_fma_f32 v[64:65], v[30:31], v[36:37], v[40:41] op_sel_hi:[1,0,1]
	v_pk_fma_f32 v[66:67], v[28:29], v[36:37], v[42:43] op_sel_hi:[1,0,1]
	ds_read_b128 v[40:43], v131 offset:1072
	v_pk_fma_f32 v[62:63], v[26:27], v[36:37], v[64:65] op_sel:[0,1,0]
	v_pk_fma_f32 v[36:37], v[24:25], v[36:37], v[66:67] op_sel:[0,1,0]
	s_waitcnt lgkmcnt(0)
	v_pk_fma_f32 v[68:69], v[30:31], v[40:41], v[44:45] op_sel_hi:[1,0,1]
	v_pk_fma_f32 v[70:71], v[28:29], v[40:41], v[46:47] op_sel_hi:[1,0,1]
	ds_read_b128 v[44:47], v131 offset:1584
	v_pk_fma_f32 v[64:65], v[26:27], v[40:41], v[68:69] op_sel:[0,1,0]
	v_pk_fma_f32 v[40:41], v[24:25], v[40:41], v[70:71] op_sel:[0,1,0]
	s_waitcnt lgkmcnt(0)
	v_pk_fma_f32 v[72:73], v[30:31], v[44:45], v[48:49] op_sel_hi:[1,0,1]
	v_pk_fma_f32 v[74:75], v[28:29], v[44:45], v[50:51] op_sel_hi:[1,0,1]
	ds_read_b128 v[48:51], v131 offset:2096
	v_pk_fma_f32 v[66:67], v[26:27], v[44:45], v[72:73] op_sel:[0,1,0]
	v_pk_fma_f32 v[44:45], v[24:25], v[44:45], v[74:75] op_sel:[0,1,0]
	s_waitcnt vmcnt(13)
	v_pk_fma_f32 v[40:41], v[20:21], v[42:43], v[40:41] op_sel_hi:[1,0,1]
	v_pk_fma_f32 v[44:45], v[20:21], v[46:47], v[44:45] op_sel_hi:[1,0,1]
	s_waitcnt lgkmcnt(0)
	v_mul_f32_e32 v48, v130, v48
	v_pk_mul_f32 v[52:53], v[14:15], v[48:49] op_sel_hi:[1,0]
	v_pk_mul_f32 v[54:55], v[12:13], v[48:49] op_sel_hi:[1,0]
	v_pk_fma_f32 v[52:53], v[98:99], v[30:31], v[52:53] op_sel_hi:[0,1,1]
	v_pk_fma_f32 v[54:55], v[98:99], v[28:29], v[54:55] op_sel_hi:[0,1,1]
	ds_read_b128 v[28:31], v131 offset:2608
	s_waitcnt lgkmcnt(0)
	v_mul_f32_e32 v28, v128, v28
	v_pk_fma_f32 v[56:57], v[8:9], v[28:29], v[54:55] op_sel_hi:[1,0,1]
	v_pk_fma_f32 v[58:59], v[10:11], v[28:29], v[52:53] op_sel_hi:[1,0,1]
	ds_read_b128 v[52:55], v131 offset:3120
	v_mul_f32_e32 v30, v128, v30
	s_waitcnt lgkmcnt(0)
	v_mul_f32_e32 v28, v129, v52
	v_pk_fma_f32 v[76:77], v[4:5], v[28:29], v[56:57] op_sel_hi:[1,0,1]
	v_pk_fma_f32 v[78:79], v[6:7], v[28:29], v[58:59] op_sel_hi:[1,0,1]
	ds_read_b128 v[56:59], v131 offset:3632
	v_mul_f32_e32 v28, v130, v49
	v_pk_mul_f32 v[48:49], v[14:15], v[28:29] op_sel_hi:[1,0]
	v_pk_mul_f32 v[68:69], v[12:13], v[28:29] op_sel_hi:[1,0]
	v_pk_fma_f32 v[26:27], v[98:99], v[26:27], v[48:49] op_sel_hi:[0,1,1]
	v_pk_fma_f32 v[24:25], v[98:99], v[24:25], v[68:69] op_sel_hi:[0,1,1]
	v_mul_f32_e32 v28, v128, v29
	v_pk_fma_f32 v[24:25], v[8:9], v[28:29], v[24:25] op_sel_hi:[1,0,1]
	v_pk_fma_f32 v[26:27], v[10:11], v[28:29], v[26:27] op_sel_hi:[1,0,1]
	v_mul_f32_e32 v28, v129, v53
	v_pk_fma_f32 v[24:25], v[4:5], v[28:29], v[24:25] op_sel_hi:[1,0,1]
	v_pk_fma_f32 v[26:27], v[6:7], v[28:29], v[26:27] op_sel_hi:[1,0,1]
	s_waitcnt lgkmcnt(0)
	v_pk_fma_f32 v[24:25], v[0:1], v[56:57], v[24:25] op_sel:[0,1,0]
	v_pk_fma_f32 v[26:27], v[2:3], v[56:57], v[26:27] op_sel:[0,1,0]
	v_lshl_add_u64 v[28:29], v[100:101], 0, v[208:209]
	global_store_dwordx4 v[28:29], v[24:27], off nt
	v_pk_fma_f32 v[76:77], v[0:1], v[56:57], v[76:77] op_sel_hi:[1,0,1]
	v_pk_fma_f32 v[78:79], v[2:3], v[56:57], v[78:79] op_sel_hi:[1,0,1]
	v_pk_fma_f32 v[24:25], v[22:23], v[34:35], v[60:61] op_sel_hi:[1,0,1]
	v_pk_fma_f32 v[26:27], v[20:21], v[34:35], v[32:33] op_sel_hi:[1,0,1]
	v_mul_f32_e32 v34, v130, v50
	v_pk_mul_f32 v[52:53], v[14:15], v[34:35] op_sel_hi:[1,0]
	v_pk_mul_f32 v[56:57], v[12:13], v[34:35] op_sel_hi:[1,0]
	v_pk_fma_f32 v[28:29], v[22:23], v[38:39], v[62:63] op_sel_hi:[1,0,1]
	v_pk_fma_f32 v[32:33], v[20:21], v[38:39], v[36:37] op_sel_hi:[1,0,1]
	v_pk_fma_f32 v[36:37], v[22:23], v[42:43], v[64:65] op_sel_hi:[1,0,1]
	v_pk_fma_f32 v[48:49], v[22:23], v[46:47], v[66:67] op_sel_hi:[1,0,1]
	v_pk_fma_f32 v[20:21], v[98:99], v[20:21], v[56:57] op_sel_hi:[0,1,1]
	v_pk_fma_f32 v[22:23], v[98:99], v[22:23], v[52:53] op_sel_hi:[0,1,1]
	v_pk_fma_f32 v[20:21], v[8:9], v[30:31], v[20:21] op_sel_hi:[1,0,1]
	v_pk_fma_f32 v[22:23], v[10:11], v[30:31], v[22:23] op_sel_hi:[1,0,1]
	v_mul_f32_e32 v30, v129, v54
	v_pk_fma_f32 v[20:21], v[4:5], v[30:31], v[20:21] op_sel_hi:[1,0,1]
	v_pk_fma_f32 v[22:23], v[6:7], v[30:31], v[22:23] op_sel_hi:[1,0,1]
	v_or_b32_e32 v208, 0x1c00, v96
	v_pk_fma_f32 v[20:21], v[0:1], v[58:59], v[20:21] op_sel_hi:[1,0,1]
	v_pk_fma_f32 v[22:23], v[2:3], v[58:59], v[22:23] op_sel_hi:[1,0,1]
	v_lshl_add_u64 v[52:53], v[100:101], 0, v[208:209]
	global_store_dwordx4 v[52:53], v[20:23], off nt
	v_or_b32_e32 v208, 0x1e00, v96
	global_store_dwordx4 v[80:81], v[76:79], off nt
	v_mov_b32_e32 v20, v35
	s_waitcnt vmcnt(15)
	v_pk_fma_f32 v[22:23], v[18:19], v[20:21], v[24:25] op_sel_hi:[1,0,1]
	v_mov_b32_e32 v24, v39
	v_pk_fma_f32 v[20:21], v[16:17], v[20:21], v[26:27] op_sel_hi:[1,0,1]
	v_pk_fma_f32 v[26:27], v[18:19], v[24:25], v[28:29] op_sel_hi:[1,0,1]
	v_mov_b32_e32 v28, v43
	v_pk_fma_f32 v[24:25], v[16:17], v[24:25], v[32:33] op_sel_hi:[1,0,1]
	v_pk_fma_f32 v[34:35], v[18:19], v[28:29], v[36:37] op_sel_hi:[1,0,1]
	v_pk_fma_f32 v[32:33], v[16:17], v[28:29], v[40:41] op_sel_hi:[1,0,1]
	v_mov_b32_e32 v28, v47
	v_pk_fma_f32 v[38:39], v[18:19], v[28:29], v[48:49] op_sel_hi:[1,0,1]
	v_pk_fma_f32 v[36:37], v[16:17], v[28:29], v[44:45] op_sel_hi:[1,0,1]
	v_mul_f32_e32 v28, v130, v51
	v_pk_mul_f32 v[14:15], v[14:15], v[28:29] op_sel_hi:[1,0]
	v_pk_mul_f32 v[12:13], v[12:13], v[28:29] op_sel_hi:[1,0]
	v_pk_fma_f32 v[14:15], v[98:99], v[18:19], v[14:15] op_sel_hi:[0,1,1]
	v_pk_fma_f32 v[12:13], v[98:99], v[16:17], v[12:13] op_sel_hi:[0,1,1]
	v_mul_f32_e32 v16, v128, v31
	v_pk_fma_f32 v[8:9], v[8:9], v[16:17], v[12:13] op_sel_hi:[1,0,1]
	v_pk_fma_f32 v[10:11], v[10:11], v[16:17], v[14:15] op_sel_hi:[1,0,1]
	v_mul_f32_e32 v12, v129, v55
	v_pk_fma_f32 v[4:5], v[4:5], v[12:13], v[8:9] op_sel_hi:[1,0,1]
	v_pk_fma_f32 v[6:7], v[6:7], v[12:13], v[10:11] op_sel_hi:[1,0,1]
	v_mov_b32_e32 v8, v59
	v_pk_fma_f32 v[0:1], v[0:1], v[8:9], v[4:5] op_sel_hi:[1,0,1]
	v_pk_fma_f32 v[2:3], v[2:3], v[8:9], v[6:7] op_sel_hi:[1,0,1]
	v_lshl_add_u64 v[4:5], v[100:101], 0, v[208:209]
	global_store_dwordx4 v[4:5], v[0:3], off nt
	v_and_b32_e32 v14, 64, v230
	v_add_u32_e32 v14, 64, v14
	v_cvt_f32_ubyte0_e32 v1, s20
	v_mul_f32_e32 v2, v124, v1
	v_cmp_gt_f32_e32 vcc, s3, v2
	v_lshl_add_u32 v0, v126, 11, v127
	ds_write_b128 v0, v[20:23] offset:8192
	ds_write_b128 v0, v[24:27] offset:8704
	ds_write_b128 v0, v[32:35] offset:9216
	ds_write_b128 v0, v[36:39] offset:9728
	v_cndmask_b32_e32 v2, 0, v233, vcc
	v_fmac_f32_e32 v2, v124, v1
	v_exp_f32_e32 v1, v2
	v_lshlrev_b32_e32 v0, 2, v125
	s_and_b64 s[20:21], vcc, exec
	v_add_u32_e32 v15, s31, v0
	s_cselect_b32 s20, 0xffffffc0, 0
	s_add_i32 s31, s31, s34
	v_add_u32_e32 v4, s31, v0
	s_waitcnt lgkmcnt(0)
	s_barrier
	v_ldexp_f32 v2, v1, s20
	ds_read2st64_b32 v[0:1], v4 offset0:32 offset1:33
	ds_read2st64_b32 v[12:13], v4 offset0:40 offset1:41
	ds_read2st64_b32 v[16:17], v4 offset0:48 offset1:49
	ds_read2st64_b32 v[18:19], v4 offset0:56 offset1:57
	ds_read2st64_b32 v[10:11], v4 offset0:64 offset1:65
	ds_read2st64_b32 v[8:9], v4 offset0:72 offset1:73
	ds_read2st64_b32 v[6:7], v4 offset0:80 offset1:81
	ds_read2st64_b32 v[4:5], v4 offset0:88 offset1:89
	s_waitcnt lgkmcnt(7)
	v_pk_add_f32 v[0:1], v[0:1], 0 op_sel_hi:[1,0]
	v_add_u32_e32 v3, s34, v15
	s_waitcnt lgkmcnt(6)
	v_pk_add_f32 v[0:1], v[0:1], v[12:13]
	s_waitcnt lgkmcnt(5)
	v_pk_add_f32 v[0:1], v[0:1], v[16:17]
	s_waitcnt lgkmcnt(4)
	v_pk_add_f32 v[12:13], v[0:1], v[18:19]
	ds_read2st64_b32 v[0:1], v3 offset1:1
	ds_read2st64_b32 v[16:17], v15 offset0:8 offset1:9
	s_waitcnt lgkmcnt(5)
	v_pk_add_f32 v[10:11], v[12:13], v[10:11]
	s_waitcnt lgkmcnt(0)
	v_pk_mul_f32 v[16:17], v[0:1], v[16:17]
	s_nop 0
	v_add_f32_e32 v3, v16, v17
	v_xor_b32_e32 v16, 1, v230
	v_cmp_lt_i32_e32 vcc, v16, v14
	v_pk_add_f32 v[8:9], v[10:11], v[8:9]
	s_nop 0
	v_cndmask_b32_e32 v16, v230, v16, vcc
	v_lshlrev_b32_e32 v16, 2, v16
	s_nop 1
	v_mov_b32_dpp v17, v3 quad_perm:[1,0,3,2] row_mask:0xf bank_mask:0xf
	v_pk_add_f32 v[6:7], v[8:9], v[6:7]
	s_waitcnt lgkmcnt(0)
	v_add_f32_e32 v3, v3, v17
	v_xor_b32_e32 v17, 2, v230
	v_cmp_lt_i32_e32 vcc, v17, v14
	v_pk_add_f32 v[4:5], v[6:7], v[4:5]
	s_nop 0
	v_cndmask_b32_e32 v17, v230, v17, vcc
	v_lshlrev_b32_e32 v17, 2, v17
	s_nop 1
	v_mov_b32_dpp v18, v3 quad_perm:[2,3,0,1] row_mask:0xf bank_mask:0xf
	s_waitcnt lgkmcnt(0)
	v_add_f32_e32 v3, v3, v18
	v_xor_b32_e32 v18, 4, v230
	v_cmp_lt_i32_e32 vcc, v18, v14
	s_nop 1
	v_cndmask_b32_e32 v18, v230, v18, vcc
	v_lshlrev_b32_e32 v18, 2, v18
	s_nop 1
	v_mov_b32_dpp v19, v3 row_half_mirror row_mask:0xf bank_mask:0xf
	s_waitcnt lgkmcnt(0)
	v_add_f32_e32 v3, v3, v19
	v_xor_b32_e32 v19, 8, v230
	v_cmp_lt_i32_e32 vcc, v19, v14
	s_nop 1
	v_cndmask_b32_e32 v19, v230, v19, vcc
	v_lshlrev_b32_e32 v19, 2, v19
	s_nop 1
	v_mov_b32_dpp v20, v3 row_mirror row_mask:0xf bank_mask:0xf
	s_waitcnt lgkmcnt(0)
	v_add_f32_e32 v3, v3, v20
	v_xor_b32_e32 v20, 16, v230
	v_cmp_lt_i32_e32 vcc, v20, v14
	s_nop 1
	v_cndmask_b32_e32 v20, v230, v20, vcc
	v_lshlrev_b32_e32 v20, 2, v20
	v_mov_b32_e32 v21, v3
	s_nop 1
	v_permlane16_swap_b32 v21, v3
	s_waitcnt lgkmcnt(0)
	v_add_f32_e32 v3, v3, v21
	v_xor_b32_e32 v21, 32, v230
	v_cmp_lt_i32_e32 vcc, v21, v14
	s_nop 1
	v_cndmask_b32_e32 v14, v230, v21, vcc
	v_lshlrev_b32_e32 v21, 2, v14
	v_mov_b32_e32 v14, v3
	s_nop 1
	v_permlane32_swap_b32 v14, v3
	s_waitcnt lgkmcnt(0)
	v_add_f32_e32 v3, v3, v14
	v_cvt_f32_ubyte0_e32 v14, s23
	v_mul_f32_e32 v22, v124, v14
	v_cmp_gt_f32_e32 vcc, s3, v22
	s_and_b64 s[20:21], vcc, exec
	s_cselect_b32 s20, 0xffffffc0, 0
	v_cndmask_b32_e32 v22, 0, v233, vcc
	v_fmac_f32_e32 v22, v124, v14
	v_exp_f32_e32 v14, v22
	ds_read2st64_b32 v[22:23], v15 offset0:16 offset1:17
	s_cmp_eq_u32 s23, 0
	v_ldexp_f32 v14, v14, s20
	v_mul_f32_e32 v14, v14, v3
	s_waitcnt lgkmcnt(0)
	v_pk_mul_f32 v[6:7], v[22:23], v[14:15] op_sel_hi:[1,0]
	s_nop 0
	v_pk_fma_f32 v[2:3], v[2:3], v[4:5], v[6:7] op_sel_hi:[0,1,1]
	s_cbranch_scc1 .LBB0_449
	ds_read2st64_b32 v[4:5], v15 offset0:10 offset1:11
	s_add_i32 s20, s23, -1
	s_waitcnt lgkmcnt(0)
	v_pk_mul_f32 v[4:5], v[0:1], v[4:5]
	s_nop 0
	v_add_f32_e32 v4, v4, v5
	s_nop 1
	v_mov_b32_dpp v5, v4 quad_perm:[1,0,3,2] row_mask:0xf bank_mask:0xf
	s_waitcnt lgkmcnt(0)
	v_add_f32_e32 v4, v4, v5
	s_nop 1
	v_mov_b32_dpp v5, v4 quad_perm:[2,3,0,1] row_mask:0xf bank_mask:0xf
	s_waitcnt lgkmcnt(0)
	v_add_f32_e32 v4, v4, v5
	s_nop 1
	v_mov_b32_dpp v5, v4 row_half_mirror row_mask:0xf bank_mask:0xf
	s_waitcnt lgkmcnt(0)
	v_add_f32_e32 v4, v4, v5
	s_nop 1
	v_mov_b32_dpp v5, v4 row_mirror row_mask:0xf bank_mask:0xf
	s_waitcnt lgkmcnt(0)
	v_add_f32_e32 v4, v4, v5
	v_mov_b32_e32 v5, v4
	s_nop 1
	v_permlane16_swap_b32 v5, v4
	s_waitcnt lgkmcnt(0)
	v_add_f32_e32 v4, v4, v5
	v_mov_b32_e32 v5, v4
	s_nop 1
	v_permlane32_swap_b32 v5, v4
	s_waitcnt lgkmcnt(0)
	v_add_f32_e32 v4, v4, v5
	v_cvt_f32_u32_e32 v5, s20
	v_mul_f32_e32 v6, v124, v5
	v_cmp_gt_f32_e32 vcc, s3, v6
	s_and_b64 s[20:21], vcc, exec
	s_cselect_b32 s20, 0xffffffc0, 0
	v_cndmask_b32_e32 v6, 0, v233, vcc
	v_fmac_f32_e32 v6, v124, v5
	v_exp_f32_e32 v5, v6
	ds_read2st64_b32 v[6:7], v15 offset0:18 offset1:19
	v_ldexp_f32 v5, v5, s20
	v_mul_f32_e32 v4, v5, v4
	s_waitcnt lgkmcnt(0)
	v_pk_fma_f32 v[2:3], v[6:7], v[4:5], v[2:3] op_sel_hi:[1,0,1]
.LBB0_449:
	s_cmp_lt_u32 s23, 2
	s_cbranch_scc1 .LBB0_451
	ds_read2st64_b32 v[4:5], v15 offset0:12 offset1:13
	s_add_i32 s20, s23, -2
	s_waitcnt lgkmcnt(0)
	v_pk_mul_f32 v[4:5], v[0:1], v[4:5]
	s_nop 0
	v_add_f32_e32 v4, v4, v5
	s_nop 1
	v_mov_b32_dpp v5, v4 quad_perm:[1,0,3,2] row_mask:0xf bank_mask:0xf
	s_waitcnt lgkmcnt(0)
	v_add_f32_e32 v4, v4, v5
	s_nop 1
	v_mov_b32_dpp v5, v4 quad_perm:[2,3,0,1] row_mask:0xf bank_mask:0xf
	s_waitcnt lgkmcnt(0)
	v_add_f32_e32 v4, v4, v5
	s_nop 1
	v_mov_b32_dpp v5, v4 row_half_mirror row_mask:0xf bank_mask:0xf
	s_waitcnt lgkmcnt(0)
	v_add_f32_e32 v4, v4, v5
	s_nop 1
	v_mov_b32_dpp v5, v4 row_mirror row_mask:0xf bank_mask:0xf
	s_waitcnt lgkmcnt(0)
	v_add_f32_e32 v4, v4, v5
	v_mov_b32_e32 v5, v4
	s_nop 1
	v_permlane16_swap_b32 v5, v4
	s_waitcnt lgkmcnt(0)
	v_add_f32_e32 v4, v4, v5
	v_mov_b32_e32 v5, v4
	s_nop 1
	v_permlane32_swap_b32 v5, v4
	s_waitcnt lgkmcnt(0)
	v_add_f32_e32 v4, v4, v5
	v_cvt_f32_u32_e32 v5, s20
	v_mul_f32_e32 v6, v124, v5
	v_cmp_gt_f32_e32 vcc, s3, v6
	s_and_b64 s[20:21], vcc, exec
	s_cselect_b32 s20, 0xffffffc0, 0
	v_cndmask_b32_e32 v6, 0, v233, vcc
	v_fmac_f32_e32 v6, v124, v5
	v_exp_f32_e32 v5, v6
	ds_read2st64_b32 v[6:7], v15 offset0:20 offset1:21
	v_ldexp_f32 v5, v5, s20
	v_mul_f32_e32 v4, v5, v4
	s_waitcnt lgkmcnt(0)
	v_pk_fma_f32 v[2:3], v[6:7], v[4:5], v[2:3] op_sel_hi:[1,0,1]
.LBB0_451:
	s_cmp_lg_u32 s23, 3
	s_cbranch_scc1 .LBB0_453
	ds_read2st64_b32 v[4:5], v15 offset0:14 offset1:15
	s_waitcnt lgkmcnt(0)
	v_pk_mul_f32 v[0:1], v[0:1], v[4:5]
	s_nop 0
	v_add_f32_e32 v0, v0, v1
	s_nop 1
	v_mov_b32_dpp v1, v0 quad_perm:[1,0,3,2] row_mask:0xf bank_mask:0xf
	ds_read2st64_b32 v[4:5], v15 offset0:22 offset1:23
	s_waitcnt lgkmcnt(0)
	v_add_f32_e32 v0, v0, v1
	s_nop 1
	v_mov_b32_dpp v1, v0 quad_perm:[2,3,0,1] row_mask:0xf bank_mask:0xf
	s_waitcnt lgkmcnt(0)
	v_add_f32_e32 v0, v0, v1
	s_nop 1
	v_mov_b32_dpp v1, v0 row_half_mirror row_mask:0xf bank_mask:0xf
	s_waitcnt lgkmcnt(0)
	v_add_f32_e32 v0, v0, v1
	s_nop 1
	v_mov_b32_dpp v1, v0 row_mirror row_mask:0xf bank_mask:0xf
	s_waitcnt lgkmcnt(0)
	v_add_f32_e32 v0, v0, v1
	v_mov_b32_e32 v1, v0
	s_nop 1
	v_permlane16_swap_b32 v1, v0
	s_waitcnt lgkmcnt(0)
	v_add_f32_e32 v0, v0, v1
	v_mov_b32_e32 v1, v0
	s_nop 1
	v_permlane32_swap_b32 v1, v0
	s_waitcnt lgkmcnt(0)
	v_add_f32_e32 v0, v0, v1
	v_mul_f32_e32 v1, 0, v124
	v_cmp_gt_f32_e32 vcc, s3, v1
	s_and_b64 s[20:21], vcc, exec
	s_cselect_b32 s20, 0xffffffc0, 0
	v_cndmask_b32_e32 v1, 0, v233, vcc
	v_fmac_f32_e32 v1, 0, v124
	v_exp_f32_e32 v1, v1
	s_nop 0
	v_ldexp_f32 v1, v1, s20
	v_mul_f32_e32 v0, v1, v0
	v_pk_fma_f32 v[2:3], v[4:5], v[0:1], v[2:3] op_sel_hi:[1,0,1]
.LBB0_453:
	s_nop 0
	v_add_f32_e32 v0, v2, v3
	s_nop 1
	v_mov_b32_dpp v1, v0 quad_perm:[1,0,3,2] row_mask:0xf bank_mask:0xf
	s_lshl_b64 s[0:1], s[0:1], 11
	s_add_u32 s0, s86, s0
	v_lshlrev_b32_e32 v5, 16, v123
	v_lshlrev_b32_e32 v4, 16, v122
	s_waitcnt lgkmcnt(0)
	v_add_f32_e32 v0, v0, v1
	s_nop 1
	v_mov_b32_dpp v1, v0 quad_perm:[2,3,0,1] row_mask:0xf bank_mask:0xf
	s_addc_u32 s1, s87, s1
	s_lshl_b32 s20, s22, 1
	s_add_u32 s0, s0, s20
	s_addc_u32 s1, s1, 0
	s_waitcnt lgkmcnt(0)
	v_add_f32_e32 v0, v0, v1
	s_nop 1
	v_mov_b32_dpp v1, v0 row_half_mirror row_mask:0xf bank_mask:0xf
	s_waitcnt lgkmcnt(0)
	v_add_f32_e32 v0, v0, v1
	s_nop 1
	v_mov_b32_dpp v1, v0 row_mirror row_mask:0xf bank_mask:0xf
	s_waitcnt lgkmcnt(0)
	v_add_f32_e32 v0, v0, v1
	v_mov_b32_e32 v1, v0
	s_nop 1
	v_permlane16_swap_b32 v1, v0
	s_waitcnt lgkmcnt(0)
	v_add_f32_e32 v0, v0, v1
	v_mov_b32_e32 v1, v0
	s_nop 1
	v_permlane32_swap_b32 v1, v0
	s_waitcnt lgkmcnt(0)
	v_add_f32_e32 v0, v0, v1
	v_mul_f32_e32 v0, 0x3c000000, v0
	v_pk_add_f32 v[0:1], v[2:3], v[0:1] op_sel_hi:[1,0] neg_lo:[0,1] neg_hi:[0,1]
	s_nop 0
	v_pk_mul_f32 v[2:3], v[0:1], v[0:1]
	s_nop 0
	v_add_f32_e32 v2, v2, v3
	s_nop 1
	v_mov_b32_dpp v3, v2 quad_perm:[1,0,3,2] row_mask:0xf bank_mask:0xf
	s_waitcnt lgkmcnt(0)
	v_add_f32_e32 v2, v2, v3
	s_nop 1
	v_mov_b32_dpp v3, v2 quad_perm:[2,3,0,1] row_mask:0xf bank_mask:0xf
	s_waitcnt lgkmcnt(0)
	v_add_f32_e32 v2, v2, v3
	s_nop 1
	v_mov_b32_dpp v3, v2 row_half_mirror row_mask:0xf bank_mask:0xf
	s_waitcnt lgkmcnt(0)
	v_add_f32_e32 v2, v2, v3
	s_nop 1
	v_mov_b32_dpp v3, v2 row_mirror row_mask:0xf bank_mask:0xf
	s_waitcnt lgkmcnt(0)
	v_add_f32_e32 v2, v2, v3
	v_mov_b32_e32 v3, v2
	s_nop 1
	v_permlane16_swap_b32 v3, v2
	s_waitcnt lgkmcnt(0)
	v_add_f32_e32 v2, v2, v3
	v_mov_b32_e32 v3, v2
	s_nop 1
	v_permlane32_swap_b32 v3, v2
	s_waitcnt lgkmcnt(0)
	v_add_f32_e32 v2, v2, v3
	v_fmamk_f32 v2, v2, 0x3c000000, v228
	v_cmp_gt_f32_e32 vcc, s69, v2
	v_mul_f32_e32 v3, 0x4b800000, v2
	s_nop 0
	v_cndmask_b32_e32 v2, v2, v3, vcc
	v_rsq_f32_e32 v2, v2
	s_nop 0
	v_mul_f32_e32 v3, 0x45800000, v2
	v_cndmask_b32_e32 v2, v2, v3, vcc
	v_pk_mul_f32 v[0:1], v[0:1], v[2:3] op_sel_hi:[1,0]
	s_nop 0
	v_pk_mul_f32 v[0:1], v[0:1], v[4:5]
	s_nop 0
	v_cvt_pk_bf16_f32 v0, v0, v1
	global_store_short v99, v0, s[0:1] offset:1024
	global_store_short_d16_hi v99, v0, s[0:1] offset:1152
	s_barrier
	s_mov_b64 s[0:1], 0

.LBB0_460:
	ds_read_b128 v[4:7], v21
	ds_read_b128 v[0:3], v21 offset:16
	s_add_i32 s0, s0, 8
	s_mov_b64 s[20:21], 0x4000
	v_add_u32_e32 v21, 0x4000, v21
	s_waitcnt lgkmcnt(1)
	v_mov_b32_e32 v22, v5
	v_mov_b32_e32 v23, v6
	v_mov_b32_e32 v24, v4
	v_mov_b32_e32 v25, v7
	v_pk_add_f32 v[22:23], v[22:23], v[24:25]
	s_waitcnt lgkmcnt(0)
	v_mov_b32_e32 v24, v2
	v_mov_b32_e32 v25, v0
	v_mov_b32_e32 v26, v3
	v_mov_b32_e32 v27, v1
	v_pk_add_f32 v[24:25], v[24:25], v[26:27]
	v_add_f32_e32 v14, v22, v23
	v_add_f32_e32 v14, v14, v25
	v_add_f32_e32 v14, v24, v14
	s_cmp_lt_i32 s0, -4
	s_nop 1
	v_add_f32_dpp v14, v14, v14 quad_perm:[1,0,3,2] row_mask:0xf bank_mask:0xf
	s_nop 1
	v_add_f32_dpp v14, v14, v14 quad_perm:[2,3,0,1] row_mask:0xf bank_mask:0xf
	s_nop 1
	v_add_f32_dpp v14, v14, v14 row_half_mirror row_mask:0xf bank_mask:0xf
	s_nop 1
	v_add_f32_dpp v14, v14, v14 row_mirror row_mask:0xf bank_mask:0xf
	v_mov_b32_e32 v22, v14
	s_nop 1
	v_permlane16_swap_b32 v22, v14
	v_add_f32_e32 v14, v14, v22
	v_mov_b32_e32 v22, v14
	s_nop 1
	v_permlane32_swap_b32 v22, v14
	v_add_f32_e32 v14, v14, v22
	v_fmamk_f32 v5, v14, 0xbb000000, v5
	v_fmamk_f32 v4, v14, 0xbb000000, v4
	v_fmamk_f32 v7, v14, 0xbb000000, v7
	v_fmac_f32_e32 v6, 0xbb000000, v14
	v_pk_mul_f32 v[22:23], v[6:7], v[6:7]
	v_pk_mul_f32 v[24:25], v[4:5], v[4:5]
	v_fmamk_f32 v1, v14, 0xbb000000, v1
	v_fmamk_f32 v0, v14, 0xbb000000, v0
	v_fmamk_f32 v3, v14, 0xbb000000, v3
	v_fmac_f32_e32 v2, 0xbb000000, v14
	v_pk_mov_b32 v[26:27], v[24:25], v[22:23] op_sel:[1,0]
	v_mov_b32_e32 v25, v23
	v_pk_add_f32 v[22:23], v[26:27], v[24:25]
	v_pk_mul_f32 v[24:25], v[2:3], v[2:3]
	v_pk_mul_f32 v[26:27], v[0:1], v[0:1]
	v_mov_b32_e32 v28, v24
	v_mov_b32_e32 v29, v26
	v_mov_b32_e32 v26, v25
	v_pk_add_f32 v[24:25], v[28:29], v[26:27]
	v_add_f32_e32 v14, v22, v23
	v_add_f32_e32 v14, v25, v14
	v_add_f32_e32 v14, v24, v14
	s_nop 1
	v_add_f32_dpp v14, v14, v14 quad_perm:[1,0,3,2] row_mask:0xf bank_mask:0xf
	s_nop 1
	v_add_f32_dpp v14, v14, v14 quad_perm:[2,3,0,1] row_mask:0xf bank_mask:0xf
	s_nop 1
	v_add_f32_dpp v14, v14, v14 row_half_mirror row_mask:0xf bank_mask:0xf
	s_nop 1
	v_add_f32_dpp v14, v14, v14 row_mirror row_mask:0xf bank_mask:0xf
	v_mov_b32_e32 v22, v14
	s_nop 1
	v_permlane16_swap_b32 v22, v14
	v_add_f32_e32 v14, v14, v22
	v_mov_b32_e32 v22, v14
	s_nop 1
	v_permlane32_swap_b32 v22, v14
	v_add_f32_e32 v14, v14, v22
	v_fmamk_f32 v14, v14, 0x3b000000, v228
	v_cmp_gt_f32_e32 vcc, s69, v14
	v_mul_f32_e32 v22, 0x4b800000, v14
	s_nop 0
	v_cndmask_b32_e32 v14, v14, v22, vcc
	v_rsq_f32_e32 v14, v14
	s_nop 0
	v_mul_f32_e32 v22, 0x45800000, v14
	v_cndmask_b32_e32 v14, v14, v22, vcc
	global_load_dwordx4 v[22:25], v[8:9], off offset:16
	global_load_dwordx4 v[26:29], v[8:9], off
	global_load_dwordx4 v[30:33], v[10:11], off offset:16
	global_load_dwordx4 v[34:37], v[10:11], off
	v_pk_mul_f32 v[4:5], v[4:5], v[14:15] op_sel_hi:[1,0]
	v_pk_mul_f32 v[6:7], v[6:7], v[14:15] op_sel_hi:[1,0]
	v_pk_mul_f32 v[0:1], v[0:1], v[14:15] op_sel_hi:[1,0]
	v_pk_mul_f32 v[2:3], v[2:3], v[14:15] op_sel_hi:[1,0]
	s_waitcnt vmcnt(1)
	v_pk_fma_f32 v[0:1], v[22:23], v[0:1], v[30:31]
	s_waitcnt vmcnt(0)
	v_pk_fma_f32 v[4:5], v[26:27], v[4:5], v[34:35]
	v_pk_fma_f32 v[2:3], v[24:25], v[2:3], v[32:33]
	v_mul_f32_e32 v14, 0xbfb8aa3b, v4
	v_exp_f32_e32 v14, v14
	v_pk_fma_f32 v[6:7], v[28:29], v[6:7], v[36:37]
	v_add_f32_e32 v14, 1.0, v14
	v_rcp_f32_e32 v22, v14
	v_mul_f32_e32 v14, 0xbfb8aa3b, v0
	v_exp_f32_e32 v14, v14
	s_nop 0
	v_add_f32_e32 v14, 1.0, v14
	v_rcp_f32_e32 v24, v14
	v_mul_f32_e32 v14, 0xbfb8aa3b, v5
	v_exp_f32_e32 v14, v14
	s_nop 0
	v_add_f32_e32 v14, 1.0, v14
	v_rcp_f32_e32 v23, v14
	v_mul_f32_e32 v14, 0xbfb8aa3b, v1
	v_exp_f32_e32 v14, v14
	v_pk_mul_f32 v[4:5], v[4:5], v[22:23]
	v_add_f32_e32 v14, 1.0, v14
	v_rcp_f32_e32 v25, v14
	s_nop 0
	v_pk_mul_f32 v[22:23], v[0:1], v[24:25]
	v_mul_f32_e32 v1, 0xbfb8aa3b, v2
	v_exp_f32_e32 v1, v1
	v_mul_f32_e32 v0, 0xbfb8aa3b, v6
	v_exp_f32_e32 v0, v0
	v_add_f32_e32 v1, 1.0, v1
	v_rcp_f32_e32 v24, v1
	v_mul_f32_e32 v1, 0xbfb8aa3b, v7
	v_exp_f32_e32 v1, v1
	v_add_f32_e32 v0, 1.0, v0
	v_rcp_f32_e32 v0, v0
	v_add_f32_e32 v1, 1.0, v1
	v_rcp_f32_e32 v1, v1
	s_nop 0
	v_pk_mul_f32 v[6:7], v[6:7], v[0:1]
	v_mul_f32_e32 v0, 0xbfb8aa3b, v3
	v_exp_f32_e32 v0, v0
	v_cvt_pk_bf16_f32 v1, v6, v7
	v_add_f32_e32 v0, 1.0, v0
	v_rcp_f32_e32 v25, v0
	v_cvt_pk_bf16_f32 v0, v4, v5
	v_pk_mul_f32 v[24:25], v[2:3], v[24:25]
	v_cvt_pk_bf16_f32 v2, v22, v23
	v_cvt_pk_bf16_f32 v3, v24, v25
	global_store_dwordx4 v[12:13], v[0:3], off
	v_lshl_add_u64 v[12:13], v[12:13], 0, s[20:21]
	s_cbranch_scc1 .LBB0_460

.LBB0_529:
	ds_read_b128 v[26:29], v24
	ds_read_b128 v[30:33], v24 offset:16
	s_add_i32 s1, s1, 4
	s_mov_b64 s[20:21], 0x2000
	v_add_u32_e32 v24, 0x2000, v24
	s_waitcnt lgkmcnt(1)
	v_mov_b32_e32 v34, v27
	v_mov_b32_e32 v35, v28
	v_mov_b32_e32 v36, v26
	v_mov_b32_e32 v37, v29
	v_pk_add_f32 v[34:35], v[34:35], v[36:37]
	s_waitcnt lgkmcnt(0)
	v_mov_b32_e32 v36, v32
	v_mov_b32_e32 v37, v30
	v_mov_b32_e32 v38, v33
	v_mov_b32_e32 v39, v31
	v_pk_add_f32 v[36:37], v[36:37], v[38:39]
	v_add_f32_e32 v25, v34, v35
	v_add_f32_e32 v25, v25, v37
	v_add_f32_e32 v25, v36, v25
	s_cmp_lt_u32 s1, 28
	s_nop 1
	v_add_f32_dpp v25, v25, v25 quad_perm:[1,0,3,2] row_mask:0xf bank_mask:0xf
	s_nop 1
	v_add_f32_dpp v25, v25, v25 quad_perm:[2,3,0,1] row_mask:0xf bank_mask:0xf
	s_nop 1
	v_add_f32_dpp v25, v25, v25 row_half_mirror row_mask:0xf bank_mask:0xf
	s_nop 1
	v_add_f32_dpp v25, v25, v25 row_mirror row_mask:0xf bank_mask:0xf
	v_mov_b32_e32 v34, v25
	s_nop 1
	v_permlane16_swap_b32 v34, v25
	v_add_f32_e32 v25, v25, v34
	v_mov_b32_e32 v34, v25
	s_nop 1
	v_permlane32_swap_b32 v34, v25
	v_add_f32_e32 v25, v25, v34
	v_fmamk_f32 v27, v25, 0xbb000000, v27
	v_fmamk_f32 v26, v25, 0xbb000000, v26
	v_fmamk_f32 v29, v25, 0xbb000000, v29
	v_fmac_f32_e32 v28, 0xbb000000, v25
	v_pk_mul_f32 v[34:35], v[28:29], v[28:29]
	v_pk_mul_f32 v[36:37], v[26:27], v[26:27]
	v_fmamk_f32 v31, v25, 0xbb000000, v31
	v_fmamk_f32 v30, v25, 0xbb000000, v30
	v_fmamk_f32 v33, v25, 0xbb000000, v33
	v_fmac_f32_e32 v32, 0xbb000000, v25
	v_pk_mov_b32 v[38:39], v[36:37], v[34:35] op_sel:[1,0]
	v_mov_b32_e32 v37, v35
	v_pk_add_f32 v[34:35], v[38:39], v[36:37]
	v_pk_mul_f32 v[36:37], v[32:33], v[32:33]
	v_pk_mul_f32 v[38:39], v[30:31], v[30:31]
	v_mov_b32_e32 v40, v36
	v_mov_b32_e32 v41, v38
	v_mov_b32_e32 v38, v37
	v_pk_add_f32 v[36:37], v[40:41], v[38:39]
	v_add_f32_e32 v25, v34, v35
	v_add_f32_e32 v25, v37, v25
	v_add_f32_e32 v25, v36, v25
	s_nop 1
	v_add_f32_dpp v25, v25, v25 quad_perm:[1,0,3,2] row_mask:0xf bank_mask:0xf
	s_nop 1
	v_add_f32_dpp v25, v25, v25 quad_perm:[2,3,0,1] row_mask:0xf bank_mask:0xf
	s_nop 1
	v_add_f32_dpp v25, v25, v25 row_half_mirror row_mask:0xf bank_mask:0xf
	s_nop 1
	v_add_f32_dpp v25, v25, v25 row_mirror row_mask:0xf bank_mask:0xf
	v_mov_b32_e32 v34, v25
	s_nop 1
	v_permlane16_swap_b32 v34, v25
	v_add_f32_e32 v25, v25, v34
	v_mov_b32_e32 v34, v25
	s_nop 1
	v_permlane32_swap_b32 v34, v25
	v_add_f32_e32 v25, v25, v34
	v_fmamk_f32 v25, v25, 0x3b000000, v228
	v_cmp_gt_f32_e32 vcc, s69, v25
	v_mul_f32_e32 v34, 0x4b800000, v25
	s_nop 0
	v_cndmask_b32_e32 v25, v25, v34, vcc
	v_rsq_f32_e32 v25, v25
	s_nop 0
	v_mul_f32_e32 v34, 0x45800000, v25
	v_cndmask_b32_e32 v34, v25, v34, vcc
	v_pk_mul_f32 v[26:27], v[26:27], v[34:35] op_sel_hi:[1,0]
	v_pk_mul_f32 v[30:31], v[30:31], v[34:35] op_sel_hi:[1,0]
	v_pk_fma_f32 v[26:27], v[4:5], v[26:27], v[12:13]
	v_pk_fma_f32 v[30:31], v[0:1], v[30:31], v[8:9]
	v_mul_f32_e32 v25, 0xbfb8aa3b, v26
	v_exp_f32_e32 v25, v25
	v_pk_mul_f32 v[28:29], v[28:29], v[34:35] op_sel_hi:[1,0]
	v_pk_mul_f32 v[32:33], v[32:33], v[34:35] op_sel_hi:[1,0]
	v_pk_fma_f32 v[28:29], v[6:7], v[28:29], v[14:15]
	v_add_f32_e32 v25, 1.0, v25
	v_rcp_f32_e32 v34, v25
	v_mul_f32_e32 v25, 0xbfb8aa3b, v30
	v_exp_f32_e32 v25, v25
	v_pk_fma_f32 v[32:33], v[2:3], v[32:33], v[10:11]
	v_add_f32_e32 v25, 1.0, v25
	v_rcp_f32_e32 v36, v25
	v_mul_f32_e32 v25, 0xbfb8aa3b, v27
	v_exp_f32_e32 v25, v25
	s_nop 0
	v_add_f32_e32 v25, 1.0, v25
	v_rcp_f32_e32 v35, v25
	v_mul_f32_e32 v25, 0xbfb8aa3b, v31
	v_exp_f32_e32 v25, v25
	v_pk_mul_f32 v[26:27], v[26:27], v[34:35]
	s_nop 0
	v_cvt_pk_bf16_f32 v26, v26, v27
	v_add_f32_e32 v25, 1.0, v25
	v_rcp_f32_e32 v37, v25
	v_mul_f32_e32 v25, 0xbfb8aa3b, v28
	v_exp_f32_e32 v25, v25
	v_pk_mul_f32 v[30:31], v[30:31], v[36:37]
	v_add_f32_e32 v25, 1.0, v25
	v_rcp_f32_e32 v34, v25
	v_mul_f32_e32 v25, 0xbfb8aa3b, v32
	v_exp_f32_e32 v25, v25
	s_nop 0
	v_add_f32_e32 v25, 1.0, v25
	v_rcp_f32_e32 v36, v25
	v_mul_f32_e32 v25, 0xbfb8aa3b, v29
	v_exp_f32_e32 v25, v25
	s_nop 0
	v_add_f32_e32 v25, 1.0, v25
	v_rcp_f32_e32 v35, v25
	v_mul_f32_e32 v25, 0xbfb8aa3b, v33
	v_exp_f32_e32 v25, v25
	v_pk_mul_f32 v[28:29], v[28:29], v[34:35]
	s_nop 0
	v_cvt_pk_bf16_f32 v27, v28, v29
	v_add_f32_e32 v25, 1.0, v25
	v_rcp_f32_e32 v37, v25
	v_cvt_pk_bf16_f32 v28, v30, v31
	v_pk_mul_f32 v[32:33], v[32:33], v[36:37]
	s_nop 0
	v_cvt_pk_bf16_f32 v29, v32, v33
	global_store_dwordx4 v[16:17], v[26:29], off
	v_lshl_add_u64 v[16:17], v[16:17], 0, s[20:21]
	s_cbranch_scc1 .LBB0_529
	s_barrier
	s_branch .LBB0_443

.LBB0_627:
	v_add3_u32 v64, v236, s17, 1
	v_cvt_f32_i32_e32 v64, v64
	s_lshl_b32 s92, s0, 1
	s_add_i32 s16, s16, s78
	s_cmpk_gt_i32 s16, 0x1ff
	v_mul_f32_e32 v65, v235, v64
	v_cmp_gt_f32_e32 vcc, s3, v65
	s_nop 1
	v_cndmask_b32_e32 v65, 0, v233, vcc
	v_fmac_f32_e32 v65, v235, v64
	v_exp_f32_e32 v64, v65
	v_cndmask_b32_e32 v65, 0, v234, vcc
	v_ldexp_f32 v64, v64, v65
	v_pk_fma_f32 v[28:29], v[64:65], v[56:57], v[28:29] op_sel_hi:[0,1,1]
	v_pk_fma_f32 v[24:25], v[64:65], v[60:61], v[24:25] op_sel_hi:[0,1,1]
	v_pk_fma_f32 v[30:31], v[64:65], v[58:59], v[30:31] op_sel_hi:[0,1,1]
	v_pk_fma_f32 v[26:27], v[64:65], v[62:63], v[26:27] op_sel_hi:[0,1,1]
	v_mov_b32_e32 v56, v24
	v_mov_b32_e32 v57, v28
	v_mov_b32_e32 v58, v25
	v_mov_b32_e32 v59, v29
	v_pk_add_f32 v[56:57], v[56:57], v[58:59]
	v_mov_b32_e32 v58, v26
	v_mov_b32_e32 v59, v30
	v_mov_b32_e32 v60, v27
	v_mov_b32_e32 v61, v31
	v_pk_fma_f32 v[18:19], v[64:65], v[46:47], v[18:19] op_sel_hi:[0,1,1]
	v_pk_fma_f32 v[16:17], v[64:65], v[44:45], v[16:17] op_sel_hi:[0,1,1]
	v_pk_add_f32 v[58:59], v[58:59], v[60:61]
	v_pk_mov_b32 v[44:45], v[16:17], v[18:19] op_sel:[1,0]
	v_mov_b32_e32 v46, v16
	v_mov_b32_e32 v47, v19
	v_pk_add_f32 v[56:57], v[56:57], v[58:59]
	v_pk_add_f32 v[44:45], v[44:45], v[46:47]
	v_add_f32_e32 v57, 0, v57
	v_pk_add_f32 v[44:45], v[44:45], v[44:45] op_sel_hi:[0,1]
	v_pk_fma_f32 v[14:15], v[64:65], v[42:43], v[14:15] op_sel_hi:[0,1,1]
	v_pk_fma_f32 v[40:41], v[64:65], v[40:41], v[12:13] op_sel_hi:[0,1,1]
	v_pk_fma_f32 v[12:13], v[64:65], v[50:51], v[22:23] op_sel_hi:[0,1,1]
	v_pk_fma_f32 v[20:21], v[64:65], v[48:49], v[20:21] op_sel_hi:[0,1,1]
	v_add_f32_e32 v57, v56, v57
	v_add_f32_e32 v43, v40, v41
	v_add_f32_e32 v47, v14, v15
	v_mov_b32_e32 v42, v20
	v_mov_b32_e32 v46, v21
	v_mov_b32_e32 v44, v12
	v_mov_b32_e32 v56, v13
	v_pk_fma_f32 v[10:11], v[64:65], v[38:39], v[10:11] op_sel_hi:[0,1,1]
	v_pk_fma_f32 v[8:9], v[64:65], v[36:37], v[8:9] op_sel_hi:[0,1,1]
	v_pk_add_f32 v[22:23], v[42:43], v[46:47]
	v_pk_add_f32 v[42:43], v[44:45], v[56:57]
	v_pk_mov_b32 v[36:37], v[8:9], v[10:11] op_sel:[1,0]
	v_mov_b32_e32 v38, v8
	v_mov_b32_e32 v39, v11
	v_pk_add_f32 v[22:23], v[22:23], v[42:43]
	v_pk_add_f32 v[36:37], v[36:37], v[38:39]
	v_pk_add_f32 v[22:23], v[22:23], v[22:23] op_sel_hi:[0,1]
	v_pk_add_f32 v[36:37], v[36:37], v[36:37] op_sel_hi:[0,1]
	v_pk_fma_f32 v[6:7], v[64:65], v[34:35], v[6:7] op_sel_hi:[0,1,1]
	v_pk_fma_f32 v[4:5], v[64:65], v[32:33], v[4:5] op_sel_hi:[0,1,1]
	v_pk_fma_f32 v[2:3], v[64:65], v[54:55], v[2:3] op_sel_hi:[0,1,1]
	v_pk_fma_f32 v[0:1], v[64:65], v[52:53], v[0:1] op_sel_hi:[0,1,1]
	v_add_f32_e32 v33, v4, v5
	v_add_f32_e32 v35, v6, v7
	v_mov_b32_e32 v32, v0
	v_mov_b32_e32 v34, v1
	v_mov_b32_e32 v36, v2
	v_mov_b32_e32 v22, v3
	v_pk_add_f32 v[32:33], v[32:33], v[34:35]
	v_pk_add_f32 v[22:23], v[36:37], v[22:23]
	s_nop 0
	v_pk_add_f32 v[22:23], v[32:33], v[22:23]
	v_and_b32_e32 v32, 64, v230
	v_add_f32_e32 v22, v22, v23
	v_xor_b32_e32 v23, 16, v230
	v_add_u32_e32 v32, 64, v32
	v_cmp_lt_i32_e32 vcc, v23, v32
	s_nop 1
	v_cndmask_b32_e32 v23, v230, v23, vcc
	v_lshlrev_b32_e32 v54, 2, v23
	v_mov_b32_e32 v23, v22
	s_nop 1
	v_permlane16_swap_b32 v23, v22
	s_waitcnt lgkmcnt(0)
	v_add_f32_e32 v22, v22, v23
	v_xor_b32_e32 v23, 32, v230
	v_cmp_lt_i32_e32 vcc, v23, v32
	s_nop 1
	v_cndmask_b32_e32 v23, v230, v23, vcc
	v_lshlrev_b32_e32 v55, 2, v23
	v_mov_b32_e32 v23, v22
	v_mov_b32_e32 v66, v22
	s_nop 1
	v_permlane32_swap_b32 v23, v66
	s_waitcnt lgkmcnt(0)
	v_add_f32_e32 v52, v66, v23
	v_fmamk_f32 v29, v52, 0xbc000000, v29
	v_fmamk_f32 v25, v52, 0xbc000000, v25
	v_fmamk_f32 v31, v52, 0xbc000000, v31
	v_fmac_f32_e32 v28, 0xbc000000, v52
	v_fmamk_f32 v27, v52, 0xbc000000, v27
	v_fmac_f32_e32 v24, 0xbc000000, v52
	v_mov_b32_e32 v32, v29
	v_mov_b32_e32 v33, v25
	v_fmac_f32_e32 v30, 0xbc000000, v52
	v_fmac_f32_e32 v26, 0xbc000000, v52
	v_mov_b32_e32 v22, v28
	v_mov_b32_e32 v23, v24
	v_pk_mul_f32 v[32:33], v[32:33], v[32:33]
	v_mov_b32_e32 v34, v31
	v_mov_b32_e32 v35, v27
	v_pk_fma_f32 v[22:23], v[22:23], v[22:23], v[32:33]
	v_mov_b32_e32 v32, v30
	v_mov_b32_e32 v33, v26
	v_pk_mul_f32 v[34:35], v[34:35], v[34:35]
	v_fmamk_f32 v17, v52, 0xbc000000, v17
	v_pk_fma_f32 v[32:33], v[32:33], v[32:33], v[34:35]
	v_fmac_f32_e32 v16, 0xbc000000, v52
	v_pk_add_f32 v[22:23], v[22:23], v[32:33]
	v_fmamk_f32 v19, v52, 0xbc000000, v19
	v_fmac_f32_e32 v18, 0xbc000000, v52
	v_pk_add_f32 v[22:23], v[22:23], v[22:23] op_sel_hi:[0,1]
	v_pk_mul_f32 v[32:33], v[18:19], v[18:19]
	v_pk_mul_f32 v[34:35], v[16:17], v[16:17]
	v_fmac_f32_e32 v40, 0xbc000000, v52
	v_pk_mov_b32 v[36:37], v[34:35], v[32:33] op_sel:[1,0]
	v_mov_b32_e32 v35, v33
	v_fmac_f32_e32 v14, 0xbc000000, v52
	v_fmamk_f32 v41, v52, 0xbc000000, v41
	v_mul_f32_e32 v22, v40, v40
	v_pk_add_f32 v[32:33], v[36:37], v[34:35]
	v_fmamk_f32 v15, v52, 0xbc000000, v15
	v_lshl_add_u64 v[34:35], s[54:55], 0, v[224:225]
	v_pk_fma_f32 v[42:43], v[40:41], v[40:41], v[22:23] op_sel_hi:[1,1,0]
	v_mul_f32_e32 v22, v14, v14
	v_pk_add_f32 v[32:33], v[32:33], v[32:33] op_sel_hi:[0,1]
	v_lshl_add_u64 v[34:35], v[34:35], 0, s[92:93]
	v_lshlrev_b64 v[36:37], 1, v[208:209]
	v_pk_fma_f32 v[44:45], v[14:15], v[14:15], v[22:23] op_sel_hi:[1,1,0]
	v_fmamk_f32 v13, v52, 0xbc000000, v13
	v_fmac_f32_e32 v12, 0xbc000000, v52
	v_fmamk_f32 v21, v52, 0xbc000000, v21
	v_fmac_f32_e32 v20, 0xbc000000, v52
	v_lshl_add_u64 v[34:35], v[34:35], 0, v[36:37]
	v_mul_f32_e32 v42, v20, v20
	v_mul_f32_e32 v44, v21, v21
	v_mul_f32_e32 v32, v12, v12
	v_mul_f32_e32 v22, v13, v13
	global_load_dwordx2 v[38:39], v[34:35], off
	global_load_dwordx2 v[46:47], v[34:35], off offset:32
	v_pk_add_f32 v[42:43], v[42:43], v[44:45]
	v_pk_add_f32 v[22:23], v[32:33], v[22:23]
	v_fmamk_f32 v9, v52, 0xbc000000, v9
	v_pk_add_f32 v[22:23], v[42:43], v[22:23]
	v_fmac_f32_e32 v8, 0xbc000000, v52
	v_fmamk_f32 v11, v52, 0xbc000000, v11
	v_fmac_f32_e32 v10, 0xbc000000, v52
	v_pk_add_f32 v[22:23], v[22:23], v[22:23] op_sel_hi:[0,1]
	v_pk_mul_f32 v[42:43], v[10:11], v[10:11]
	v_pk_mul_f32 v[44:45], v[8:9], v[8:9]
	v_fmac_f32_e32 v4, 0xbc000000, v52
	v_pk_mov_b32 v[48:49], v[44:45], v[42:43] op_sel:[1,0]
	v_mov_b32_e32 v45, v43
	v_fmac_f32_e32 v6, 0xbc000000, v52
	v_fmamk_f32 v5, v52, 0xbc000000, v5
	v_mul_f32_e32 v22, v4, v4
	v_pk_add_f32 v[42:43], v[48:49], v[44:45]
	v_fmamk_f32 v7, v52, 0xbc000000, v7
	v_pk_fma_f32 v[48:49], v[4:5], v[4:5], v[22:23] op_sel_hi:[1,1,0]
	v_mul_f32_e32 v22, v6, v6
	v_pk_add_f32 v[42:43], v[42:43], v[42:43] op_sel_hi:[0,1]
	v_pk_fma_f32 v[50:51], v[6:7], v[6:7], v[22:23] op_sel_hi:[1,1,0]
	v_fmamk_f32 v3, v52, 0xbc000000, v3
	v_fmac_f32_e32 v2, 0xbc000000, v52
	v_fmamk_f32 v1, v52, 0xbc000000, v1
	v_fmac_f32_e32 v0, 0xbc000000, v52
	v_mul_f32_e32 v48, v0, v0
	v_mul_f32_e32 v50, v1, v1
	v_mul_f32_e32 v42, v2, v2
	v_mul_f32_e32 v22, v3, v3
	global_load_dwordx2 v[32:33], v[34:35], off offset:64
	global_load_dwordx2 v[44:45], v[34:35], off offset:96
	v_pk_add_f32 v[48:49], v[48:49], v[50:51]
	v_pk_add_f32 v[22:23], v[42:43], v[22:23]
	global_load_dwordx2 v[52:53], v[34:35], off offset:128
	v_pk_add_f32 v[22:23], v[48:49], v[22:23]
	v_lshlrev_b64 v[50:51], 11, v[222:223]
	v_add_f32_e32 v42, v22, v23
	v_mov_b32_e32 v43, v42
	s_nop 1
	v_permlane16_swap_b32 v43, v42
	global_load_dwordx2 v[22:23], v[34:35], off offset:160
	v_lshl_add_u64 v[50:51], s[86:87], 0, v[50:51]
	v_lshl_add_u64 v[50:51], v[50:51], 0, s[92:93]
	v_lshl_add_u64 v[36:37], v[50:51], 0, v[36:37]
	s_waitcnt lgkmcnt(0)
	v_add_f32_e32 v42, v42, v43
	v_mov_b32_e32 v43, v42
	s_nop 1
	v_permlane32_swap_b32 v43, v42
	s_waitcnt lgkmcnt(0)
	v_add_f32_e32 v42, v42, v43
	v_fmamk_f32 v48, v42, 0x3c000000, v228
	global_load_dwordx2 v[42:43], v[34:35], off offset:192
	v_mul_f32_e32 v49, 0x4b800000, v48
	global_load_dwordx2 v[34:35], v[34:35], off offset:224
	v_cmp_gt_f32_e32 vcc, s69, v48
	s_waitcnt vmcnt(7)
	v_lshlrev_b32_e32 v50, 16, v38
	v_cndmask_b32_e32 v48, v48, v49, vcc
	v_rsq_f32_e32 v48, v48
	v_and_b32_e32 v51, 0xffff0000, v38
	v_lshlrev_b32_e32 v38, 16, v39
	v_and_b32_e32 v39, 0xffff0000, v39
	v_mul_f32_e32 v49, 0x45800000, v48
	v_cndmask_b32_e32 v48, v48, v49, vcc
	v_pk_mul_f32 v[28:29], v[28:29], v[48:49] op_sel_hi:[1,0]
	v_pk_mul_f32 v[30:31], v[30:31], v[48:49] op_sel_hi:[1,0]
	v_pk_mul_f32 v[28:29], v[28:29], v[50:51]
	v_pk_mul_f32 v[30:31], v[30:31], v[38:39]
	v_cvt_pk_bf16_f32 v28, v28, v29
	v_cvt_pk_bf16_f32 v29, v30, v31
	global_store_dwordx2 v[36:37], v[28:29], off offset:1024
	v_pk_mul_f32 v[24:25], v[24:25], v[48:49] op_sel_hi:[1,0]
	s_waitcnt vmcnt(7)
	v_lshlrev_b32_e32 v28, 16, v46
	v_and_b32_e32 v29, 0xffff0000, v46
	v_pk_mul_f32 v[24:25], v[24:25], v[28:29]
	v_pk_mul_f32 v[26:27], v[26:27], v[48:49] op_sel_hi:[1,0]
	v_lshlrev_b32_e32 v28, 16, v47
	v_and_b32_e32 v29, 0xffff0000, v47
	v_pk_mul_f32 v[26:27], v[26:27], v[28:29]
	v_cvt_pk_bf16_f32 v24, v24, v25
	v_cvt_pk_bf16_f32 v25, v26, v27
	global_store_dwordx2 v[36:37], v[24:25], off offset:1056
	v_pk_mul_f32 v[16:17], v[16:17], v[48:49] op_sel_hi:[1,0]
	v_pk_mul_f32 v[18:19], v[18:19], v[48:49] op_sel_hi:[1,0]
	v_pk_mul_f32 v[14:15], v[14:15], v[48:49] op_sel_hi:[1,0]
	v_pk_mul_f32 v[12:13], v[12:13], v[48:49] op_sel_hi:[1,0]
	v_pk_mul_f32 v[8:9], v[8:9], v[48:49] op_sel_hi:[1,0]
	v_pk_mul_f32 v[10:11], v[10:11], v[48:49] op_sel_hi:[1,0]
	s_waitcnt vmcnt(7)
	v_lshlrev_b32_e32 v24, 16, v32
	v_and_b32_e32 v25, 0xffff0000, v32
	v_pk_mul_f32 v[16:17], v[16:17], v[24:25]
	v_lshlrev_b32_e32 v24, 16, v33
	v_and_b32_e32 v25, 0xffff0000, v33
	v_pk_mul_f32 v[18:19], v[18:19], v[24:25]
	v_cvt_pk_bf16_f32 v16, v16, v17
	v_cvt_pk_bf16_f32 v17, v18, v19
	global_store_dwordx2 v[36:37], v[16:17], off offset:1088
	v_pk_mul_f32 v[16:17], v[40:41], v[48:49] op_sel_hi:[1,0]
	s_waitcnt vmcnt(7)
	v_lshlrev_b32_e32 v18, 16, v44
	v_and_b32_e32 v19, 0xffff0000, v44
	v_pk_mul_f32 v[16:17], v[16:17], v[18:19]
	v_lshlrev_b32_e32 v18, 16, v45
	v_and_b32_e32 v19, 0xffff0000, v45
	v_pk_mul_f32 v[14:15], v[14:15], v[18:19]
	v_cvt_pk_bf16_f32 v16, v16, v17
	v_cvt_pk_bf16_f32 v17, v14, v15
	global_store_dwordx2 v[36:37], v[16:17], off offset:1120
	v_pk_mul_f32 v[14:15], v[20:21], v[48:49] op_sel_hi:[1,0]
	s_waitcnt vmcnt(7)
	v_lshlrev_b32_e32 v16, 16, v52
	v_and_b32_e32 v17, 0xffff0000, v52
	v_pk_mul_f32 v[14:15], v[14:15], v[16:17]
	v_lshlrev_b32_e32 v16, 16, v53
	v_and_b32_e32 v17, 0xffff0000, v53
	v_pk_mul_f32 v[12:13], v[12:13], v[16:17]
	v_cvt_pk_bf16_f32 v14, v14, v15
	v_cvt_pk_bf16_f32 v15, v12, v13
	s_waitcnt vmcnt(6)
	v_lshlrev_b32_e32 v12, 16, v22
	v_and_b32_e32 v13, 0xffff0000, v22
	v_pk_mul_f32 v[8:9], v[8:9], v[12:13]
	v_lshlrev_b32_e32 v12, 16, v23
	v_and_b32_e32 v13, 0xffff0000, v23
	v_pk_mul_f32 v[10:11], v[10:11], v[12:13]
	v_cvt_pk_bf16_f32 v8, v8, v9
	v_cvt_pk_bf16_f32 v9, v10, v11
	global_store_dwordx2 v[36:37], v[8:9], off offset:1184
	v_pk_mul_f32 v[4:5], v[4:5], v[48:49] op_sel_hi:[1,0]
	s_waitcnt vmcnt(6)
	v_lshlrev_b32_e32 v8, 16, v42
	v_and_b32_e32 v9, 0xffff0000, v42
	v_pk_mul_f32 v[4:5], v[4:5], v[8:9]
	v_pk_mul_f32 v[6:7], v[6:7], v[48:49] op_sel_hi:[1,0]
	v_lshlrev_b32_e32 v8, 16, v43
	v_and_b32_e32 v9, 0xffff0000, v43
	v_pk_mul_f32 v[6:7], v[6:7], v[8:9]
	v_cvt_pk_bf16_f32 v4, v4, v5
	v_cvt_pk_bf16_f32 v5, v6, v7
	global_store_dwordx2 v[36:37], v[4:5], off offset:1216
	v_pk_mul_f32 v[0:1], v[0:1], v[48:49] op_sel_hi:[1,0]
	s_waitcnt vmcnt(6)
	v_lshlrev_b32_e32 v4, 16, v34
	v_and_b32_e32 v5, 0xffff0000, v34
	v_pk_mul_f32 v[0:1], v[0:1], v[4:5]
	v_pk_mul_f32 v[2:3], v[2:3], v[48:49] op_sel_hi:[1,0]
	v_lshlrev_b32_e32 v4, 16, v35
	v_and_b32_e32 v5, 0xffff0000, v35
	v_pk_mul_f32 v[2:3], v[2:3], v[4:5]
	v_cvt_pk_bf16_f32 v0, v0, v1
	v_cvt_pk_bf16_f32 v1, v2, v3
	global_store_dwordx2 v[36:37], v[14:15], off offset:1152
	global_store_dwordx2 v[36:37], v[0:1], off offset:1248
	s_barrier
	s_cbranch_scc1 .LBB0_623
